# skinny-GEMM item (f + rope-key columns): K-loop rewritten with SGPR bases, immediate K offsets, in-place fragment refill and counted waits instead of ~9 dependent round trips per 2 steps
# baseline (speedup 1.0000x reference)
.LBB0_425:
	s_andn2_b64 vcc, exec, s[0:1]
	s_cbranch_vccnz .LBB0_430
	v_readlane_b32 s0, v254, 1
	v_readlane_b32 s1, v254, 2
	s_andn2_b64 vcc, exec, s[0:1]
	s_cbranch_vccnz .LBB0_430
	v_mov_b32_e32 v180, v0
	s_movk_i32 s0, 0x100
	s_mov_b32 s1, s41
	s_mov_b32 s2, s43
	s_lshl_b32 s0, s2, 9
	v_and_b32_e32 v5, 15, v180
	s_ashr_i32 s1, s0, 31
	s_mov_b64 s[22:23], s[84:85]
	s_mul_i32 s3, s70, 0xc0000
	v_lshlrev_b32_e32 v2, 13, v5
	v_and_b32_e32 v6, 48, v180
	s_lshl_b64 s[0:1], s[0:1], 1
	v_or3_b32 v2, s3, v2, v6
	s_add_u32 s6, s22, s0
	v_or_b32_e32 v6, s0, v6
	v_readlane_b32 s0, v254, 4
	v_mov_b32_e32 v7, s1
	v_mov_b32_e32 v9, v4
	v_add_lshl_u32 v8, s0, v5, 13
	v_mov_b32_e32 v3, v4
	s_addc_u32 s7, s23, s1
	v_lshl_add_u64 v[6:7], v[6:7], 0, v[8:9]
	v_mov_b32_e32 v58, 0
	v_lshrrev_b32_e32 v181, 4, v180
	v_lshl_add_u64 v[2:3], s[6:7], 0, v[2:3]
	v_lshl_add_u64 v[166:167], s[22:23], 0, v[6:7]
	s_mov_b64 s[24:25], 0
	v_mov_b32_e32 v59, v58
	v_mov_b32_e32 v60, v58
	v_mov_b32_e32 v61, v58
	v_mov_b32_e32 v66, v58
	v_mov_b32_e32 v67, v58
	v_mov_b32_e32 v68, v58
	v_mov_b32_e32 v69, v58
	s_waitcnt vmcnt(2)
	v_mov_b32_e32 v74, v58
	v_mov_b32_e32 v75, v58
	v_mov_b32_e32 v76, v58
	v_mov_b32_e32 v77, v58
	v_mov_b32_e32 v82, v58
	v_mov_b32_e32 v83, v58
	v_mov_b32_e32 v84, v58
	v_mov_b32_e32 v85, v58
	v_mov_b32_e32 v90, v58
	v_mov_b32_e32 v91, v58
	v_mov_b32_e32 v92, v58
	v_mov_b32_e32 v93, v58
	v_mov_b32_e32 v98, v58
	v_mov_b32_e32 v99, v58
	v_mov_b32_e32 v100, v58
	v_mov_b32_e32 v101, v58
	v_mov_b32_e32 v54, v58
	v_mov_b32_e32 v55, v58
	v_mov_b32_e32 v56, v58
	v_mov_b32_e32 v57, v58
	v_mov_b32_e32 v62, v58
	v_mov_b32_e32 v63, v58
	v_mov_b32_e32 v64, v58
	v_mov_b32_e32 v65, v58
	s_waitcnt vmcnt(1)
	v_mov_b32_e32 v70, v58
	v_mov_b32_e32 v71, v58
	v_mov_b32_e32 v72, v58
	v_mov_b32_e32 v73, v58
	v_mov_b32_e32 v78, v58
	v_mov_b32_e32 v79, v58
	v_mov_b32_e32 v80, v58
	v_mov_b32_e32 v81, v58
	v_mov_b32_e32 v86, v58
	v_mov_b32_e32 v87, v58
	v_mov_b32_e32 v88, v58
	v_mov_b32_e32 v89, v58
	v_mov_b32_e32 v94, v58
	v_mov_b32_e32 v95, v58
	v_mov_b32_e32 v96, v58
	v_mov_b32_e32 v97, v58
	v_mov_b32_e32 v106, v58
	v_mov_b32_e32 v107, v58
	v_mov_b32_e32 v108, v58
	v_mov_b32_e32 v109, v58
	v_mov_b32_e32 v110, v58
	v_mov_b32_e32 v111, v58
	v_mov_b32_e32 v112, v58
	v_mov_b32_e32 v113, v58
	v_mov_b32_e32 v114, v58
	v_mov_b32_e32 v115, v58
	v_mov_b32_e32 v116, v58
	v_mov_b32_e32 v117, v58
	v_mov_b32_e32 v130, v58
	v_mov_b32_e32 v131, v58
	v_mov_b32_e32 v132, v58
	v_mov_b32_e32 v133, v58
	v_mov_b32_e32 v142, v58
	v_mov_b32_e32 v143, v58
	v_mov_b32_e32 v144, v58
	v_mov_b32_e32 v145, v58
	v_mov_b32_e32 v146, v58
	v_mov_b32_e32 v147, v58
	v_mov_b32_e32 v148, v58
	v_mov_b32_e32 v149, v58
	v_mov_b32_e32 v118, v58
	v_mov_b32_e32 v119, v58
	v_mov_b32_e32 v120, v58
	v_mov_b32_e32 v121, v58
	v_mov_b32_e32 v122, v58
	v_mov_b32_e32 v123, v58
	v_mov_b32_e32 v124, v58
	v_mov_b32_e32 v125, v58
	v_mov_b32_e32 v126, v58
	v_mov_b32_e32 v127, v58
	v_mov_b32_e32 v128, v58
	v_mov_b32_e32 v129, v58
	v_mov_b32_e32 v134, v58
	v_mov_b32_e32 v135, v58
	v_mov_b32_e32 v136, v58
	v_mov_b32_e32 v137, v58
	v_mov_b32_e32 v138, v58
	v_mov_b32_e32 v139, v58
	v_mov_b32_e32 v140, v58
	v_mov_b32_e32 v141, v58
	v_mov_b32_e32 v102, v58
	v_mov_b32_e32 v103, v58
	v_mov_b32_e32 v104, v58
	v_mov_b32_e32 v105, v58
	v_mov_b32_e32 v10, v58
	v_mov_b32_e32 v11, v58
	v_mov_b32_e32 v12, v58
	v_mov_b32_e32 v13, v58
	v_mov_b32_e32 v14, v58
	v_mov_b32_e32 v15, v58
	v_mov_b32_e32 v16, v58
	v_mov_b32_e32 v17, v58
	v_mov_b32_e32 v18, v58
	v_mov_b32_e32 v19, v58
	v_mov_b32_e32 v20, v58
	v_mov_b32_e32 v21, v58
	v_mov_b32_e32 v22, v58
	v_mov_b32_e32 v23, v58
	v_mov_b32_e32 v24, v58
	v_mov_b32_e32 v25, v58
	v_mov_b32_e32 v26, v58
	v_mov_b32_e32 v27, v58
	v_mov_b32_e32 v28, v58
	v_mov_b32_e32 v29, v58
	v_mov_b32_e32 v6, v58
	v_mov_b32_e32 v7, v58
	v_mov_b32_e32 v8, v58
	v_mov_b32_e32 v9, v58
	v_mov_b32_e32 v34, v58
	v_mov_b32_e32 v35, v58
	v_mov_b32_e32 v36, v58
	v_mov_b32_e32 v37, v58
	v_mov_b32_e32 v38, v58
	v_mov_b32_e32 v39, v58
	v_mov_b32_e32 v40, v58
	v_mov_b32_e32 v41, v58
	v_mov_b32_e32 v42, v58
	v_mov_b32_e32 v43, v58
	v_mov_b32_e32 v44, v58
	v_mov_b32_e32 v45, v58
	v_mov_b32_e32 v46, v58
	v_mov_b32_e32 v47, v58
	v_mov_b32_e32 v48, v58
	v_mov_b32_e32 v49, v58
	v_mov_b32_e32 v50, v58
	v_mov_b32_e32 v51, v58
	v_mov_b32_e32 v52, v58
	v_mov_b32_e32 v53, v58
	v_mov_b32_e32 v30, v58
	v_mov_b32_e32 v31, v58
	v_mov_b32_e32 v32, v58
	v_mov_b32_e32 v33, v58
	v_readfirstlane_b32 s0, v166
	v_readfirstlane_b32 s1, v167
	v_readfirstlane_b32 s24, v2
	v_readfirstlane_b32 s25, v3
	s_nop 4
	v_subrev_u32_e32 v176, s0, v166
	s_add_u32 s6, s0, 0x10f80000
	s_addc_u32 s7, s1, 0
	s_add_u32 s8, s0, 0x10fa0000
	s_addc_u32 s9, s1, 0
	s_add_u32 s10, s0, 0x10fc0000
	s_addc_u32 s11, s1, 0
	s_add_u32 s12, s0, 0x10fe0000
	s_addc_u32 s13, s1, 0
	s_add_u32 s14, s0, 0x11000000
	s_addc_u32 s15, s1, 0
	s_add_u32 s16, s0, 0x11020000
	s_addc_u32 s17, s1, 0
	s_add_u32 s26, s24, 0xba20000
	s_addc_u32 s27, s25, 0
	s_add_u32 s28, s24, 0xba40000
	s_addc_u32 s29, s25, 0
	s_add_u32 s30, s24, 0xba60000
	s_addc_u32 s31, s25, 0
	s_add_u32 s34, s24, 0xba80000
	s_addc_u32 s35, s25, 0
	s_add_u32 s0, s24, 0xbaa0000
	s_addc_u32 s1, s25, 0
	s_add_u32 s24, s24, 0xba00000
	s_addc_u32 s25, s25, 0
	global_load_dwordx4 v[182:185], v176, s[24:25]
	global_load_dwordx4 v[186:189], v176, s[26:27]
	global_load_dwordx4 v[190:193], v176, s[28:29]
	global_load_dwordx4 v[194:197], v176, s[30:31]
	global_load_dwordx4 v[198:201], v176, s[34:35]
	global_load_dwordx4 v[202:205], v176, s[0:1]
	global_load_dwordx4 v[150:153], v176, s[6:7]
	global_load_dwordx4 v[154:157], v176, s[8:9]
	global_load_dwordx4 v[158:161], v176, s[10:11]
	global_load_dwordx4 v[162:165], v176, s[12:13]
	global_load_dwordx4 v[168:171], v176, s[14:15]
	global_load_dwordx4 v[172:175], v176, s[16:17]
	s_waitcnt vmcnt(5)
	v_mfma_f32_16x16x32_bf16 v[102:105], v[182:185], v[150:153], v[102:105]
	v_mfma_f32_16x16x32_bf16 v[138:141], v[186:189], v[150:153], v[138:141]
	v_mfma_f32_16x16x32_bf16 v[134:137], v[190:193], v[150:153], v[134:137]
	v_mfma_f32_16x16x32_bf16 v[126:129], v[194:197], v[150:153], v[126:129]
	v_mfma_f32_16x16x32_bf16 v[122:125], v[198:201], v[150:153], v[122:125]
	v_mfma_f32_16x16x32_bf16 v[118:121], v[202:205], v[150:153], v[118:121]
	global_load_dwordx4 v[150:153], v176, s[6:7] offset:64
	s_waitcnt vmcnt(5)
	v_mfma_f32_16x16x32_bf16 v[146:149], v[182:185], v[154:157], v[146:149]
	v_mfma_f32_16x16x32_bf16 v[142:145], v[186:189], v[154:157], v[142:145]
	v_mfma_f32_16x16x32_bf16 v[130:133], v[190:193], v[154:157], v[130:133]
	v_mfma_f32_16x16x32_bf16 v[114:117], v[194:197], v[154:157], v[114:117]
	v_mfma_f32_16x16x32_bf16 v[110:113], v[198:201], v[154:157], v[110:113]
	v_mfma_f32_16x16x32_bf16 v[106:109], v[202:205], v[154:157], v[106:109]
	global_load_dwordx4 v[154:157], v176, s[8:9] offset:64
	s_waitcnt vmcnt(5)
	v_mfma_f32_16x16x32_bf16 v[94:97], v[182:185], v[158:161], v[94:97]
	v_mfma_f32_16x16x32_bf16 v[86:89], v[186:189], v[158:161], v[86:89]
	v_mfma_f32_16x16x32_bf16 v[78:81], v[190:193], v[158:161], v[78:81]
	v_mfma_f32_16x16x32_bf16 v[70:73], v[194:197], v[158:161], v[70:73]
	v_mfma_f32_16x16x32_bf16 v[62:65], v[198:201], v[158:161], v[62:65]
	v_mfma_f32_16x16x32_bf16 v[54:57], v[202:205], v[158:161], v[54:57]
	global_load_dwordx4 v[158:161], v176, s[10:11] offset:64
	s_waitcnt vmcnt(5)
	v_mfma_f32_16x16x32_bf16 v[98:101], v[182:185], v[162:165], v[98:101]
	v_mfma_f32_16x16x32_bf16 v[90:93], v[186:189], v[162:165], v[90:93]
	v_mfma_f32_16x16x32_bf16 v[82:85], v[190:193], v[162:165], v[82:85]
	v_mfma_f32_16x16x32_bf16 v[74:77], v[194:197], v[162:165], v[74:77]
	v_mfma_f32_16x16x32_bf16 v[66:69], v[198:201], v[162:165], v[66:69]
	v_mfma_f32_16x16x32_bf16 v[58:61], v[202:205], v[162:165], v[58:61]
	global_load_dwordx4 v[162:165], v176, s[12:13] offset:64
	s_waitcnt vmcnt(5)
	v_mfma_f32_16x16x32_bf16 v[10:13], v[182:185], v[168:171], v[10:13]
	v_mfma_f32_16x16x32_bf16 v[14:17], v[186:189], v[168:171], v[14:17]
	v_mfma_f32_16x16x32_bf16 v[18:21], v[190:193], v[168:171], v[18:21]
	v_mfma_f32_16x16x32_bf16 v[22:25], v[194:197], v[168:171], v[22:25]
	v_mfma_f32_16x16x32_bf16 v[26:29], v[198:201], v[168:171], v[26:29]
	v_mfma_f32_16x16x32_bf16 v[6:9], v[202:205], v[168:171], v[6:9]
	global_load_dwordx4 v[168:171], v176, s[14:15] offset:64
	s_waitcnt vmcnt(5)
	v_mfma_f32_16x16x32_bf16 v[34:37], v[182:185], v[172:175], v[34:37]
	global_load_dwordx4 v[182:185], v176, s[24:25] offset:64
	v_mfma_f32_16x16x32_bf16 v[38:41], v[186:189], v[172:175], v[38:41]
	global_load_dwordx4 v[186:189], v176, s[26:27] offset:64
	v_mfma_f32_16x16x32_bf16 v[42:45], v[190:193], v[172:175], v[42:45]
	global_load_dwordx4 v[190:193], v176, s[28:29] offset:64
	v_mfma_f32_16x16x32_bf16 v[46:49], v[194:197], v[172:175], v[46:49]
	global_load_dwordx4 v[194:197], v176, s[30:31] offset:64
	v_mfma_f32_16x16x32_bf16 v[50:53], v[198:201], v[172:175], v[50:53]
	global_load_dwordx4 v[198:201], v176, s[34:35] offset:64
	v_mfma_f32_16x16x32_bf16 v[30:33], v[202:205], v[172:175], v[30:33]
	global_load_dwordx4 v[202:205], v176, s[0:1] offset:64
	global_load_dwordx4 v[172:175], v176, s[16:17] offset:64
	s_waitcnt vmcnt(11)
	s_waitcnt vmcnt(6)
	v_mfma_f32_16x16x32_bf16 v[102:105], v[182:185], v[150:153], v[102:105]
	s_waitcnt vmcnt(5)
	v_mfma_f32_16x16x32_bf16 v[138:141], v[186:189], v[150:153], v[138:141]
	s_waitcnt vmcnt(4)
	v_mfma_f32_16x16x32_bf16 v[134:137], v[190:193], v[150:153], v[134:137]
	s_waitcnt vmcnt(3)
	v_mfma_f32_16x16x32_bf16 v[126:129], v[194:197], v[150:153], v[126:129]
	s_waitcnt vmcnt(2)
	v_mfma_f32_16x16x32_bf16 v[122:125], v[198:201], v[150:153], v[122:125]
	s_waitcnt vmcnt(1)
	v_mfma_f32_16x16x32_bf16 v[118:121], v[202:205], v[150:153], v[118:121]
	global_load_dwordx4 v[150:153], v176, s[6:7] offset:128
	v_mfma_f32_16x16x32_bf16 v[146:149], v[182:185], v[154:157], v[146:149]
	v_mfma_f32_16x16x32_bf16 v[142:145], v[186:189], v[154:157], v[142:145]
	v_mfma_f32_16x16x32_bf16 v[130:133], v[190:193], v[154:157], v[130:133]
	v_mfma_f32_16x16x32_bf16 v[114:117], v[194:197], v[154:157], v[114:117]
	v_mfma_f32_16x16x32_bf16 v[110:113], v[198:201], v[154:157], v[110:113]
	v_mfma_f32_16x16x32_bf16 v[106:109], v[202:205], v[154:157], v[106:109]
	global_load_dwordx4 v[154:157], v176, s[8:9] offset:128
	v_mfma_f32_16x16x32_bf16 v[94:97], v[182:185], v[158:161], v[94:97]
	v_mfma_f32_16x16x32_bf16 v[86:89], v[186:189], v[158:161], v[86:89]
	v_mfma_f32_16x16x32_bf16 v[78:81], v[190:193], v[158:161], v[78:81]
	v_mfma_f32_16x16x32_bf16 v[70:73], v[194:197], v[158:161], v[70:73]
	v_mfma_f32_16x16x32_bf16 v[62:65], v[198:201], v[158:161], v[62:65]
	v_mfma_f32_16x16x32_bf16 v[54:57], v[202:205], v[158:161], v[54:57]
	global_load_dwordx4 v[158:161], v176, s[10:11] offset:128
	v_mfma_f32_16x16x32_bf16 v[98:101], v[182:185], v[162:165], v[98:101]
	v_mfma_f32_16x16x32_bf16 v[90:93], v[186:189], v[162:165], v[90:93]
	v_mfma_f32_16x16x32_bf16 v[82:85], v[190:193], v[162:165], v[82:85]
	v_mfma_f32_16x16x32_bf16 v[74:77], v[194:197], v[162:165], v[74:77]
	v_mfma_f32_16x16x32_bf16 v[66:69], v[198:201], v[162:165], v[66:69]
	v_mfma_f32_16x16x32_bf16 v[58:61], v[202:205], v[162:165], v[58:61]
	global_load_dwordx4 v[162:165], v176, s[12:13] offset:128
	v_mfma_f32_16x16x32_bf16 v[10:13], v[182:185], v[168:171], v[10:13]
	v_mfma_f32_16x16x32_bf16 v[14:17], v[186:189], v[168:171], v[14:17]
	v_mfma_f32_16x16x32_bf16 v[18:21], v[190:193], v[168:171], v[18:21]
	v_mfma_f32_16x16x32_bf16 v[22:25], v[194:197], v[168:171], v[22:25]
	v_mfma_f32_16x16x32_bf16 v[26:29], v[198:201], v[168:171], v[26:29]
	v_mfma_f32_16x16x32_bf16 v[6:9], v[202:205], v[168:171], v[6:9]
	global_load_dwordx4 v[168:171], v176, s[14:15] offset:128
	s_waitcnt vmcnt(5)
	v_mfma_f32_16x16x32_bf16 v[34:37], v[182:185], v[172:175], v[34:37]
	global_load_dwordx4 v[182:185], v176, s[24:25] offset:128
	v_mfma_f32_16x16x32_bf16 v[38:41], v[186:189], v[172:175], v[38:41]
	global_load_dwordx4 v[186:189], v176, s[26:27] offset:128
	v_mfma_f32_16x16x32_bf16 v[42:45], v[190:193], v[172:175], v[42:45]
	global_load_dwordx4 v[190:193], v176, s[28:29] offset:128
	v_mfma_f32_16x16x32_bf16 v[46:49], v[194:197], v[172:175], v[46:49]
	global_load_dwordx4 v[194:197], v176, s[30:31] offset:128
	v_mfma_f32_16x16x32_bf16 v[50:53], v[198:201], v[172:175], v[50:53]
	global_load_dwordx4 v[198:201], v176, s[34:35] offset:128
	v_mfma_f32_16x16x32_bf16 v[30:33], v[202:205], v[172:175], v[30:33]
	global_load_dwordx4 v[202:205], v176, s[0:1] offset:128
	global_load_dwordx4 v[172:175], v176, s[16:17] offset:128
	s_waitcnt vmcnt(11)
	s_waitcnt vmcnt(6)
	v_mfma_f32_16x16x32_bf16 v[102:105], v[182:185], v[150:153], v[102:105]
	s_waitcnt vmcnt(5)
	v_mfma_f32_16x16x32_bf16 v[138:141], v[186:189], v[150:153], v[138:141]
	s_waitcnt vmcnt(4)
	v_mfma_f32_16x16x32_bf16 v[134:137], v[190:193], v[150:153], v[134:137]
	s_waitcnt vmcnt(3)
	v_mfma_f32_16x16x32_bf16 v[126:129], v[194:197], v[150:153], v[126:129]
	s_waitcnt vmcnt(2)
	v_mfma_f32_16x16x32_bf16 v[122:125], v[198:201], v[150:153], v[122:125]
	s_waitcnt vmcnt(1)
	v_mfma_f32_16x16x32_bf16 v[118:121], v[202:205], v[150:153], v[118:121]
	global_load_dwordx4 v[150:153], v176, s[6:7] offset:192
	v_mfma_f32_16x16x32_bf16 v[146:149], v[182:185], v[154:157], v[146:149]
	v_mfma_f32_16x16x32_bf16 v[142:145], v[186:189], v[154:157], v[142:145]
	v_mfma_f32_16x16x32_bf16 v[130:133], v[190:193], v[154:157], v[130:133]
	v_mfma_f32_16x16x32_bf16 v[114:117], v[194:197], v[154:157], v[114:117]
	v_mfma_f32_16x16x32_bf16 v[110:113], v[198:201], v[154:157], v[110:113]
	v_mfma_f32_16x16x32_bf16 v[106:109], v[202:205], v[154:157], v[106:109]
	global_load_dwordx4 v[154:157], v176, s[8:9] offset:192
	v_mfma_f32_16x16x32_bf16 v[94:97], v[182:185], v[158:161], v[94:97]
	v_mfma_f32_16x16x32_bf16 v[86:89], v[186:189], v[158:161], v[86:89]
	v_mfma_f32_16x16x32_bf16 v[78:81], v[190:193], v[158:161], v[78:81]
	v_mfma_f32_16x16x32_bf16 v[70:73], v[194:197], v[158:161], v[70:73]
	v_mfma_f32_16x16x32_bf16 v[62:65], v[198:201], v[158:161], v[62:65]
	v_mfma_f32_16x16x32_bf16 v[54:57], v[202:205], v[158:161], v[54:57]
	global_load_dwordx4 v[158:161], v176, s[10:11] offset:192
	v_mfma_f32_16x16x32_bf16 v[98:101], v[182:185], v[162:165], v[98:101]
	v_mfma_f32_16x16x32_bf16 v[90:93], v[186:189], v[162:165], v[90:93]
	v_mfma_f32_16x16x32_bf16 v[82:85], v[190:193], v[162:165], v[82:85]
	v_mfma_f32_16x16x32_bf16 v[74:77], v[194:197], v[162:165], v[74:77]
	v_mfma_f32_16x16x32_bf16 v[66:69], v[198:201], v[162:165], v[66:69]
	v_mfma_f32_16x16x32_bf16 v[58:61], v[202:205], v[162:165], v[58:61]
	global_load_dwordx4 v[162:165], v176, s[12:13] offset:192
	v_mfma_f32_16x16x32_bf16 v[10:13], v[182:185], v[168:171], v[10:13]
	v_mfma_f32_16x16x32_bf16 v[14:17], v[186:189], v[168:171], v[14:17]
	v_mfma_f32_16x16x32_bf16 v[18:21], v[190:193], v[168:171], v[18:21]
	v_mfma_f32_16x16x32_bf16 v[22:25], v[194:197], v[168:171], v[22:25]
	v_mfma_f32_16x16x32_bf16 v[26:29], v[198:201], v[168:171], v[26:29]
	v_mfma_f32_16x16x32_bf16 v[6:9], v[202:205], v[168:171], v[6:9]
	global_load_dwordx4 v[168:171], v176, s[14:15] offset:192
	s_waitcnt vmcnt(5)
	v_mfma_f32_16x16x32_bf16 v[34:37], v[182:185], v[172:175], v[34:37]
	global_load_dwordx4 v[182:185], v176, s[24:25] offset:192
	v_mfma_f32_16x16x32_bf16 v[38:41], v[186:189], v[172:175], v[38:41]
	global_load_dwordx4 v[186:189], v176, s[26:27] offset:192
	v_mfma_f32_16x16x32_bf16 v[42:45], v[190:193], v[172:175], v[42:45]
	global_load_dwordx4 v[190:193], v176, s[28:29] offset:192
	v_mfma_f32_16x16x32_bf16 v[46:49], v[194:197], v[172:175], v[46:49]
	global_load_dwordx4 v[194:197], v176, s[30:31] offset:192
	v_mfma_f32_16x16x32_bf16 v[50:53], v[198:201], v[172:175], v[50:53]
	global_load_dwordx4 v[198:201], v176, s[34:35] offset:192
	v_mfma_f32_16x16x32_bf16 v[30:33], v[202:205], v[172:175], v[30:33]
	global_load_dwordx4 v[202:205], v176, s[0:1] offset:192
	global_load_dwordx4 v[172:175], v176, s[16:17] offset:192
	s_waitcnt vmcnt(11)
	s_waitcnt vmcnt(6)
	v_mfma_f32_16x16x32_bf16 v[102:105], v[182:185], v[150:153], v[102:105]
	s_waitcnt vmcnt(5)
	v_mfma_f32_16x16x32_bf16 v[138:141], v[186:189], v[150:153], v[138:141]
	s_waitcnt vmcnt(4)
	v_mfma_f32_16x16x32_bf16 v[134:137], v[190:193], v[150:153], v[134:137]
	s_waitcnt vmcnt(3)
	v_mfma_f32_16x16x32_bf16 v[126:129], v[194:197], v[150:153], v[126:129]
	s_waitcnt vmcnt(2)
	v_mfma_f32_16x16x32_bf16 v[122:125], v[198:201], v[150:153], v[122:125]
	s_waitcnt vmcnt(1)
	v_mfma_f32_16x16x32_bf16 v[118:121], v[202:205], v[150:153], v[118:121]
	global_load_dwordx4 v[150:153], v176, s[6:7] offset:256
	v_mfma_f32_16x16x32_bf16 v[146:149], v[182:185], v[154:157], v[146:149]
	v_mfma_f32_16x16x32_bf16 v[142:145], v[186:189], v[154:157], v[142:145]
	v_mfma_f32_16x16x32_bf16 v[130:133], v[190:193], v[154:157], v[130:133]
	v_mfma_f32_16x16x32_bf16 v[114:117], v[194:197], v[154:157], v[114:117]
	v_mfma_f32_16x16x32_bf16 v[110:113], v[198:201], v[154:157], v[110:113]
	v_mfma_f32_16x16x32_bf16 v[106:109], v[202:205], v[154:157], v[106:109]
	global_load_dwordx4 v[154:157], v176, s[8:9] offset:256
	v_mfma_f32_16x16x32_bf16 v[94:97], v[182:185], v[158:161], v[94:97]
	v_mfma_f32_16x16x32_bf16 v[86:89], v[186:189], v[158:161], v[86:89]
	v_mfma_f32_16x16x32_bf16 v[78:81], v[190:193], v[158:161], v[78:81]
	v_mfma_f32_16x16x32_bf16 v[70:73], v[194:197], v[158:161], v[70:73]
	v_mfma_f32_16x16x32_bf16 v[62:65], v[198:201], v[158:161], v[62:65]
	v_mfma_f32_16x16x32_bf16 v[54:57], v[202:205], v[158:161], v[54:57]
	global_load_dwordx4 v[158:161], v176, s[10:11] offset:256
	v_mfma_f32_16x16x32_bf16 v[98:101], v[182:185], v[162:165], v[98:101]
	v_mfma_f32_16x16x32_bf16 v[90:93], v[186:189], v[162:165], v[90:93]
	v_mfma_f32_16x16x32_bf16 v[82:85], v[190:193], v[162:165], v[82:85]
	v_mfma_f32_16x16x32_bf16 v[74:77], v[194:197], v[162:165], v[74:77]
	v_mfma_f32_16x16x32_bf16 v[66:69], v[198:201], v[162:165], v[66:69]
	v_mfma_f32_16x16x32_bf16 v[58:61], v[202:205], v[162:165], v[58:61]
	global_load_dwordx4 v[162:165], v176, s[12:13] offset:256
	v_mfma_f32_16x16x32_bf16 v[10:13], v[182:185], v[168:171], v[10:13]
	v_mfma_f32_16x16x32_bf16 v[14:17], v[186:189], v[168:171], v[14:17]
	v_mfma_f32_16x16x32_bf16 v[18:21], v[190:193], v[168:171], v[18:21]
	v_mfma_f32_16x16x32_bf16 v[22:25], v[194:197], v[168:171], v[22:25]
	v_mfma_f32_16x16x32_bf16 v[26:29], v[198:201], v[168:171], v[26:29]
	v_mfma_f32_16x16x32_bf16 v[6:9], v[202:205], v[168:171], v[6:9]
	global_load_dwordx4 v[168:171], v176, s[14:15] offset:256
	s_waitcnt vmcnt(5)
	v_mfma_f32_16x16x32_bf16 v[34:37], v[182:185], v[172:175], v[34:37]
	global_load_dwordx4 v[182:185], v176, s[24:25] offset:256
	v_mfma_f32_16x16x32_bf16 v[38:41], v[186:189], v[172:175], v[38:41]
	global_load_dwordx4 v[186:189], v176, s[26:27] offset:256
	v_mfma_f32_16x16x32_bf16 v[42:45], v[190:193], v[172:175], v[42:45]
	global_load_dwordx4 v[190:193], v176, s[28:29] offset:256
	v_mfma_f32_16x16x32_bf16 v[46:49], v[194:197], v[172:175], v[46:49]
	global_load_dwordx4 v[194:197], v176, s[30:31] offset:256
	v_mfma_f32_16x16x32_bf16 v[50:53], v[198:201], v[172:175], v[50:53]
	global_load_dwordx4 v[198:201], v176, s[34:35] offset:256
	v_mfma_f32_16x16x32_bf16 v[30:33], v[202:205], v[172:175], v[30:33]
	global_load_dwordx4 v[202:205], v176, s[0:1] offset:256
	global_load_dwordx4 v[172:175], v176, s[16:17] offset:256
	s_waitcnt vmcnt(11)
	s_waitcnt vmcnt(6)
	v_mfma_f32_16x16x32_bf16 v[102:105], v[182:185], v[150:153], v[102:105]
	s_waitcnt vmcnt(5)
	v_mfma_f32_16x16x32_bf16 v[138:141], v[186:189], v[150:153], v[138:141]
	s_waitcnt vmcnt(4)
	v_mfma_f32_16x16x32_bf16 v[134:137], v[190:193], v[150:153], v[134:137]
	s_waitcnt vmcnt(3)
	v_mfma_f32_16x16x32_bf16 v[126:129], v[194:197], v[150:153], v[126:129]
	s_waitcnt vmcnt(2)
	v_mfma_f32_16x16x32_bf16 v[122:125], v[198:201], v[150:153], v[122:125]
	s_waitcnt vmcnt(1)
	v_mfma_f32_16x16x32_bf16 v[118:121], v[202:205], v[150:153], v[118:121]
	global_load_dwordx4 v[150:153], v176, s[6:7] offset:320
	v_mfma_f32_16x16x32_bf16 v[146:149], v[182:185], v[154:157], v[146:149]
	v_mfma_f32_16x16x32_bf16 v[142:145], v[186:189], v[154:157], v[142:145]
	v_mfma_f32_16x16x32_bf16 v[130:133], v[190:193], v[154:157], v[130:133]
	v_mfma_f32_16x16x32_bf16 v[114:117], v[194:197], v[154:157], v[114:117]
	v_mfma_f32_16x16x32_bf16 v[110:113], v[198:201], v[154:157], v[110:113]
	v_mfma_f32_16x16x32_bf16 v[106:109], v[202:205], v[154:157], v[106:109]
	global_load_dwordx4 v[154:157], v176, s[8:9] offset:320
	v_mfma_f32_16x16x32_bf16 v[94:97], v[182:185], v[158:161], v[94:97]
	v_mfma_f32_16x16x32_bf16 v[86:89], v[186:189], v[158:161], v[86:89]
	v_mfma_f32_16x16x32_bf16 v[78:81], v[190:193], v[158:161], v[78:81]
	v_mfma_f32_16x16x32_bf16 v[70:73], v[194:197], v[158:161], v[70:73]
	v_mfma_f32_16x16x32_bf16 v[62:65], v[198:201], v[158:161], v[62:65]
	v_mfma_f32_16x16x32_bf16 v[54:57], v[202:205], v[158:161], v[54:57]
	global_load_dwordx4 v[158:161], v176, s[10:11] offset:320
	v_mfma_f32_16x16x32_bf16 v[98:101], v[182:185], v[162:165], v[98:101]
	v_mfma_f32_16x16x32_bf16 v[90:93], v[186:189], v[162:165], v[90:93]
	v_mfma_f32_16x16x32_bf16 v[82:85], v[190:193], v[162:165], v[82:85]
	v_mfma_f32_16x16x32_bf16 v[74:77], v[194:197], v[162:165], v[74:77]
	v_mfma_f32_16x16x32_bf16 v[66:69], v[198:201], v[162:165], v[66:69]
	v_mfma_f32_16x16x32_bf16 v[58:61], v[202:205], v[162:165], v[58:61]
	global_load_dwordx4 v[162:165], v176, s[12:13] offset:320
	v_mfma_f32_16x16x32_bf16 v[10:13], v[182:185], v[168:171], v[10:13]
	v_mfma_f32_16x16x32_bf16 v[14:17], v[186:189], v[168:171], v[14:17]
	v_mfma_f32_16x16x32_bf16 v[18:21], v[190:193], v[168:171], v[18:21]
	v_mfma_f32_16x16x32_bf16 v[22:25], v[194:197], v[168:171], v[22:25]
	v_mfma_f32_16x16x32_bf16 v[26:29], v[198:201], v[168:171], v[26:29]
	v_mfma_f32_16x16x32_bf16 v[6:9], v[202:205], v[168:171], v[6:9]
	global_load_dwordx4 v[168:171], v176, s[14:15] offset:320
	s_waitcnt vmcnt(5)
	v_mfma_f32_16x16x32_bf16 v[34:37], v[182:185], v[172:175], v[34:37]
	global_load_dwordx4 v[182:185], v176, s[24:25] offset:320
	v_mfma_f32_16x16x32_bf16 v[38:41], v[186:189], v[172:175], v[38:41]
	global_load_dwordx4 v[186:189], v176, s[26:27] offset:320
	v_mfma_f32_16x16x32_bf16 v[42:45], v[190:193], v[172:175], v[42:45]
	global_load_dwordx4 v[190:193], v176, s[28:29] offset:320
	v_mfma_f32_16x16x32_bf16 v[46:49], v[194:197], v[172:175], v[46:49]
	global_load_dwordx4 v[194:197], v176, s[30:31] offset:320
	v_mfma_f32_16x16x32_bf16 v[50:53], v[198:201], v[172:175], v[50:53]
	global_load_dwordx4 v[198:201], v176, s[34:35] offset:320
	v_mfma_f32_16x16x32_bf16 v[30:33], v[202:205], v[172:175], v[30:33]
	global_load_dwordx4 v[202:205], v176, s[0:1] offset:320
	global_load_dwordx4 v[172:175], v176, s[16:17] offset:320
	s_waitcnt vmcnt(11)
	s_waitcnt vmcnt(6)
	v_mfma_f32_16x16x32_bf16 v[102:105], v[182:185], v[150:153], v[102:105]
	s_waitcnt vmcnt(5)
	v_mfma_f32_16x16x32_bf16 v[138:141], v[186:189], v[150:153], v[138:141]
	s_waitcnt vmcnt(4)
	v_mfma_f32_16x16x32_bf16 v[134:137], v[190:193], v[150:153], v[134:137]
	s_waitcnt vmcnt(3)
	v_mfma_f32_16x16x32_bf16 v[126:129], v[194:197], v[150:153], v[126:129]
	s_waitcnt vmcnt(2)
	v_mfma_f32_16x16x32_bf16 v[122:125], v[198:201], v[150:153], v[122:125]
	s_waitcnt vmcnt(1)
	v_mfma_f32_16x16x32_bf16 v[118:121], v[202:205], v[150:153], v[118:121]
	global_load_dwordx4 v[150:153], v176, s[6:7] offset:384
	v_mfma_f32_16x16x32_bf16 v[146:149], v[182:185], v[154:157], v[146:149]
	v_mfma_f32_16x16x32_bf16 v[142:145], v[186:189], v[154:157], v[142:145]
	v_mfma_f32_16x16x32_bf16 v[130:133], v[190:193], v[154:157], v[130:133]
	v_mfma_f32_16x16x32_bf16 v[114:117], v[194:197], v[154:157], v[114:117]
	v_mfma_f32_16x16x32_bf16 v[110:113], v[198:201], v[154:157], v[110:113]
	v_mfma_f32_16x16x32_bf16 v[106:109], v[202:205], v[154:157], v[106:109]
	global_load_dwordx4 v[154:157], v176, s[8:9] offset:384
	v_mfma_f32_16x16x32_bf16 v[94:97], v[182:185], v[158:161], v[94:97]
	v_mfma_f32_16x16x32_bf16 v[86:89], v[186:189], v[158:161], v[86:89]
	v_mfma_f32_16x16x32_bf16 v[78:81], v[190:193], v[158:161], v[78:81]
	v_mfma_f32_16x16x32_bf16 v[70:73], v[194:197], v[158:161], v[70:73]
	v_mfma_f32_16x16x32_bf16 v[62:65], v[198:201], v[158:161], v[62:65]
	v_mfma_f32_16x16x32_bf16 v[54:57], v[202:205], v[158:161], v[54:57]
	global_load_dwordx4 v[158:161], v176, s[10:11] offset:384
	v_mfma_f32_16x16x32_bf16 v[98:101], v[182:185], v[162:165], v[98:101]
	v_mfma_f32_16x16x32_bf16 v[90:93], v[186:189], v[162:165], v[90:93]
	v_mfma_f32_16x16x32_bf16 v[82:85], v[190:193], v[162:165], v[82:85]
	v_mfma_f32_16x16x32_bf16 v[74:77], v[194:197], v[162:165], v[74:77]
	v_mfma_f32_16x16x32_bf16 v[66:69], v[198:201], v[162:165], v[66:69]
	v_mfma_f32_16x16x32_bf16 v[58:61], v[202:205], v[162:165], v[58:61]
	global_load_dwordx4 v[162:165], v176, s[12:13] offset:384
	v_mfma_f32_16x16x32_bf16 v[10:13], v[182:185], v[168:171], v[10:13]
	v_mfma_f32_16x16x32_bf16 v[14:17], v[186:189], v[168:171], v[14:17]
	v_mfma_f32_16x16x32_bf16 v[18:21], v[190:193], v[168:171], v[18:21]
	v_mfma_f32_16x16x32_bf16 v[22:25], v[194:197], v[168:171], v[22:25]
	v_mfma_f32_16x16x32_bf16 v[26:29], v[198:201], v[168:171], v[26:29]
	v_mfma_f32_16x16x32_bf16 v[6:9], v[202:205], v[168:171], v[6:9]
	global_load_dwordx4 v[168:171], v176, s[14:15] offset:384
	s_waitcnt vmcnt(5)
	v_mfma_f32_16x16x32_bf16 v[34:37], v[182:185], v[172:175], v[34:37]
	global_load_dwordx4 v[182:185], v176, s[24:25] offset:384
	v_mfma_f32_16x16x32_bf16 v[38:41], v[186:189], v[172:175], v[38:41]
	global_load_dwordx4 v[186:189], v176, s[26:27] offset:384
	v_mfma_f32_16x16x32_bf16 v[42:45], v[190:193], v[172:175], v[42:45]
	global_load_dwordx4 v[190:193], v176, s[28:29] offset:384
	v_mfma_f32_16x16x32_bf16 v[46:49], v[194:197], v[172:175], v[46:49]
	global_load_dwordx4 v[194:197], v176, s[30:31] offset:384
	v_mfma_f32_16x16x32_bf16 v[50:53], v[198:201], v[172:175], v[50:53]
	global_load_dwordx4 v[198:201], v176, s[34:35] offset:384
	v_mfma_f32_16x16x32_bf16 v[30:33], v[202:205], v[172:175], v[30:33]
	global_load_dwordx4 v[202:205], v176, s[0:1] offset:384
	global_load_dwordx4 v[172:175], v176, s[16:17] offset:384
	s_waitcnt vmcnt(11)
	s_waitcnt vmcnt(6)
	v_mfma_f32_16x16x32_bf16 v[102:105], v[182:185], v[150:153], v[102:105]
	s_waitcnt vmcnt(5)
	v_mfma_f32_16x16x32_bf16 v[138:141], v[186:189], v[150:153], v[138:141]
	s_waitcnt vmcnt(4)
	v_mfma_f32_16x16x32_bf16 v[134:137], v[190:193], v[150:153], v[134:137]
	s_waitcnt vmcnt(3)
	v_mfma_f32_16x16x32_bf16 v[126:129], v[194:197], v[150:153], v[126:129]
	s_waitcnt vmcnt(2)
	v_mfma_f32_16x16x32_bf16 v[122:125], v[198:201], v[150:153], v[122:125]
	s_waitcnt vmcnt(1)
	v_mfma_f32_16x16x32_bf16 v[118:121], v[202:205], v[150:153], v[118:121]
	global_load_dwordx4 v[150:153], v176, s[6:7] offset:448
	v_mfma_f32_16x16x32_bf16 v[146:149], v[182:185], v[154:157], v[146:149]
	v_mfma_f32_16x16x32_bf16 v[142:145], v[186:189], v[154:157], v[142:145]
	v_mfma_f32_16x16x32_bf16 v[130:133], v[190:193], v[154:157], v[130:133]
	v_mfma_f32_16x16x32_bf16 v[114:117], v[194:197], v[154:157], v[114:117]
	v_mfma_f32_16x16x32_bf16 v[110:113], v[198:201], v[154:157], v[110:113]
	v_mfma_f32_16x16x32_bf16 v[106:109], v[202:205], v[154:157], v[106:109]
	global_load_dwordx4 v[154:157], v176, s[8:9] offset:448
	v_mfma_f32_16x16x32_bf16 v[94:97], v[182:185], v[158:161], v[94:97]
	v_mfma_f32_16x16x32_bf16 v[86:89], v[186:189], v[158:161], v[86:89]
	v_mfma_f32_16x16x32_bf16 v[78:81], v[190:193], v[158:161], v[78:81]
	v_mfma_f32_16x16x32_bf16 v[70:73], v[194:197], v[158:161], v[70:73]
	v_mfma_f32_16x16x32_bf16 v[62:65], v[198:201], v[158:161], v[62:65]
	v_mfma_f32_16x16x32_bf16 v[54:57], v[202:205], v[158:161], v[54:57]
	global_load_dwordx4 v[158:161], v176, s[10:11] offset:448
	v_mfma_f32_16x16x32_bf16 v[98:101], v[182:185], v[162:165], v[98:101]
	v_mfma_f32_16x16x32_bf16 v[90:93], v[186:189], v[162:165], v[90:93]
	v_mfma_f32_16x16x32_bf16 v[82:85], v[190:193], v[162:165], v[82:85]
	v_mfma_f32_16x16x32_bf16 v[74:77], v[194:197], v[162:165], v[74:77]
	v_mfma_f32_16x16x32_bf16 v[66:69], v[198:201], v[162:165], v[66:69]
	v_mfma_f32_16x16x32_bf16 v[58:61], v[202:205], v[162:165], v[58:61]
	global_load_dwordx4 v[162:165], v176, s[12:13] offset:448
	v_mfma_f32_16x16x32_bf16 v[10:13], v[182:185], v[168:171], v[10:13]
	v_mfma_f32_16x16x32_bf16 v[14:17], v[186:189], v[168:171], v[14:17]
	v_mfma_f32_16x16x32_bf16 v[18:21], v[190:193], v[168:171], v[18:21]
	v_mfma_f32_16x16x32_bf16 v[22:25], v[194:197], v[168:171], v[22:25]
	v_mfma_f32_16x16x32_bf16 v[26:29], v[198:201], v[168:171], v[26:29]
	v_mfma_f32_16x16x32_bf16 v[6:9], v[202:205], v[168:171], v[6:9]
	global_load_dwordx4 v[168:171], v176, s[14:15] offset:448
	s_waitcnt vmcnt(5)
	v_mfma_f32_16x16x32_bf16 v[34:37], v[182:185], v[172:175], v[34:37]
	global_load_dwordx4 v[182:185], v176, s[24:25] offset:448
	v_mfma_f32_16x16x32_bf16 v[38:41], v[186:189], v[172:175], v[38:41]
	global_load_dwordx4 v[186:189], v176, s[26:27] offset:448
	v_mfma_f32_16x16x32_bf16 v[42:45], v[190:193], v[172:175], v[42:45]
	global_load_dwordx4 v[190:193], v176, s[28:29] offset:448
	v_mfma_f32_16x16x32_bf16 v[46:49], v[194:197], v[172:175], v[46:49]
	global_load_dwordx4 v[194:197], v176, s[30:31] offset:448
	v_mfma_f32_16x16x32_bf16 v[50:53], v[198:201], v[172:175], v[50:53]
	global_load_dwordx4 v[198:201], v176, s[34:35] offset:448
	v_mfma_f32_16x16x32_bf16 v[30:33], v[202:205], v[172:175], v[30:33]
	global_load_dwordx4 v[202:205], v176, s[0:1] offset:448
	global_load_dwordx4 v[172:175], v176, s[16:17] offset:448
	s_waitcnt vmcnt(11)
	s_waitcnt vmcnt(6)
	v_mfma_f32_16x16x32_bf16 v[102:105], v[182:185], v[150:153], v[102:105]
	s_waitcnt vmcnt(5)
	v_mfma_f32_16x16x32_bf16 v[138:141], v[186:189], v[150:153], v[138:141]
	s_waitcnt vmcnt(4)
	v_mfma_f32_16x16x32_bf16 v[134:137], v[190:193], v[150:153], v[134:137]
	s_waitcnt vmcnt(3)
	v_mfma_f32_16x16x32_bf16 v[126:129], v[194:197], v[150:153], v[126:129]
	s_waitcnt vmcnt(2)
	v_mfma_f32_16x16x32_bf16 v[122:125], v[198:201], v[150:153], v[122:125]
	s_waitcnt vmcnt(1)
	v_mfma_f32_16x16x32_bf16 v[118:121], v[202:205], v[150:153], v[118:121]
	global_load_dwordx4 v[150:153], v176, s[6:7] offset:512
	v_mfma_f32_16x16x32_bf16 v[146:149], v[182:185], v[154:157], v[146:149]
	v_mfma_f32_16x16x32_bf16 v[142:145], v[186:189], v[154:157], v[142:145]
	v_mfma_f32_16x16x32_bf16 v[130:133], v[190:193], v[154:157], v[130:133]
	v_mfma_f32_16x16x32_bf16 v[114:117], v[194:197], v[154:157], v[114:117]
	v_mfma_f32_16x16x32_bf16 v[110:113], v[198:201], v[154:157], v[110:113]
	v_mfma_f32_16x16x32_bf16 v[106:109], v[202:205], v[154:157], v[106:109]
	global_load_dwordx4 v[154:157], v176, s[8:9] offset:512
	v_mfma_f32_16x16x32_bf16 v[94:97], v[182:185], v[158:161], v[94:97]
	v_mfma_f32_16x16x32_bf16 v[86:89], v[186:189], v[158:161], v[86:89]
	v_mfma_f32_16x16x32_bf16 v[78:81], v[190:193], v[158:161], v[78:81]
	v_mfma_f32_16x16x32_bf16 v[70:73], v[194:197], v[158:161], v[70:73]
	v_mfma_f32_16x16x32_bf16 v[62:65], v[198:201], v[158:161], v[62:65]
	v_mfma_f32_16x16x32_bf16 v[54:57], v[202:205], v[158:161], v[54:57]
	global_load_dwordx4 v[158:161], v176, s[10:11] offset:512
	v_mfma_f32_16x16x32_bf16 v[98:101], v[182:185], v[162:165], v[98:101]
	v_mfma_f32_16x16x32_bf16 v[90:93], v[186:189], v[162:165], v[90:93]
	v_mfma_f32_16x16x32_bf16 v[82:85], v[190:193], v[162:165], v[82:85]
	v_mfma_f32_16x16x32_bf16 v[74:77], v[194:197], v[162:165], v[74:77]
	v_mfma_f32_16x16x32_bf16 v[66:69], v[198:201], v[162:165], v[66:69]
	v_mfma_f32_16x16x32_bf16 v[58:61], v[202:205], v[162:165], v[58:61]
	global_load_dwordx4 v[162:165], v176, s[12:13] offset:512
	v_mfma_f32_16x16x32_bf16 v[10:13], v[182:185], v[168:171], v[10:13]
	v_mfma_f32_16x16x32_bf16 v[14:17], v[186:189], v[168:171], v[14:17]
	v_mfma_f32_16x16x32_bf16 v[18:21], v[190:193], v[168:171], v[18:21]
	v_mfma_f32_16x16x32_bf16 v[22:25], v[194:197], v[168:171], v[22:25]
	v_mfma_f32_16x16x32_bf16 v[26:29], v[198:201], v[168:171], v[26:29]
	v_mfma_f32_16x16x32_bf16 v[6:9], v[202:205], v[168:171], v[6:9]
	global_load_dwordx4 v[168:171], v176, s[14:15] offset:512
	s_waitcnt vmcnt(5)
	v_mfma_f32_16x16x32_bf16 v[34:37], v[182:185], v[172:175], v[34:37]
	global_load_dwordx4 v[182:185], v176, s[24:25] offset:512
	v_mfma_f32_16x16x32_bf16 v[38:41], v[186:189], v[172:175], v[38:41]
	global_load_dwordx4 v[186:189], v176, s[26:27] offset:512
	v_mfma_f32_16x16x32_bf16 v[42:45], v[190:193], v[172:175], v[42:45]
	global_load_dwordx4 v[190:193], v176, s[28:29] offset:512
	v_mfma_f32_16x16x32_bf16 v[46:49], v[194:197], v[172:175], v[46:49]
	global_load_dwordx4 v[194:197], v176, s[30:31] offset:512
	v_mfma_f32_16x16x32_bf16 v[50:53], v[198:201], v[172:175], v[50:53]
	global_load_dwordx4 v[198:201], v176, s[34:35] offset:512
	v_mfma_f32_16x16x32_bf16 v[30:33], v[202:205], v[172:175], v[30:33]
	global_load_dwordx4 v[202:205], v176, s[0:1] offset:512
	global_load_dwordx4 v[172:175], v176, s[16:17] offset:512
	s_waitcnt vmcnt(11)
	s_waitcnt vmcnt(6)
	v_mfma_f32_16x16x32_bf16 v[102:105], v[182:185], v[150:153], v[102:105]
	s_waitcnt vmcnt(5)
	v_mfma_f32_16x16x32_bf16 v[138:141], v[186:189], v[150:153], v[138:141]
	s_waitcnt vmcnt(4)
	v_mfma_f32_16x16x32_bf16 v[134:137], v[190:193], v[150:153], v[134:137]
	s_waitcnt vmcnt(3)
	v_mfma_f32_16x16x32_bf16 v[126:129], v[194:197], v[150:153], v[126:129]
	s_waitcnt vmcnt(2)
	v_mfma_f32_16x16x32_bf16 v[122:125], v[198:201], v[150:153], v[122:125]
	s_waitcnt vmcnt(1)
	v_mfma_f32_16x16x32_bf16 v[118:121], v[202:205], v[150:153], v[118:121]
	global_load_dwordx4 v[150:153], v176, s[6:7] offset:576
	v_mfma_f32_16x16x32_bf16 v[146:149], v[182:185], v[154:157], v[146:149]
	v_mfma_f32_16x16x32_bf16 v[142:145], v[186:189], v[154:157], v[142:145]
	v_mfma_f32_16x16x32_bf16 v[130:133], v[190:193], v[154:157], v[130:133]
	v_mfma_f32_16x16x32_bf16 v[114:117], v[194:197], v[154:157], v[114:117]
	v_mfma_f32_16x16x32_bf16 v[110:113], v[198:201], v[154:157], v[110:113]
	v_mfma_f32_16x16x32_bf16 v[106:109], v[202:205], v[154:157], v[106:109]
	global_load_dwordx4 v[154:157], v176, s[8:9] offset:576
	v_mfma_f32_16x16x32_bf16 v[94:97], v[182:185], v[158:161], v[94:97]
	v_mfma_f32_16x16x32_bf16 v[86:89], v[186:189], v[158:161], v[86:89]
	v_mfma_f32_16x16x32_bf16 v[78:81], v[190:193], v[158:161], v[78:81]
	v_mfma_f32_16x16x32_bf16 v[70:73], v[194:197], v[158:161], v[70:73]
	v_mfma_f32_16x16x32_bf16 v[62:65], v[198:201], v[158:161], v[62:65]
	v_mfma_f32_16x16x32_bf16 v[54:57], v[202:205], v[158:161], v[54:57]
	global_load_dwordx4 v[158:161], v176, s[10:11] offset:576
	v_mfma_f32_16x16x32_bf16 v[98:101], v[182:185], v[162:165], v[98:101]
	v_mfma_f32_16x16x32_bf16 v[90:93], v[186:189], v[162:165], v[90:93]
	v_mfma_f32_16x16x32_bf16 v[82:85], v[190:193], v[162:165], v[82:85]
	v_mfma_f32_16x16x32_bf16 v[74:77], v[194:197], v[162:165], v[74:77]
	v_mfma_f32_16x16x32_bf16 v[66:69], v[198:201], v[162:165], v[66:69]
	v_mfma_f32_16x16x32_bf16 v[58:61], v[202:205], v[162:165], v[58:61]
	global_load_dwordx4 v[162:165], v176, s[12:13] offset:576
	v_mfma_f32_16x16x32_bf16 v[10:13], v[182:185], v[168:171], v[10:13]
	v_mfma_f32_16x16x32_bf16 v[14:17], v[186:189], v[168:171], v[14:17]
	v_mfma_f32_16x16x32_bf16 v[18:21], v[190:193], v[168:171], v[18:21]
	v_mfma_f32_16x16x32_bf16 v[22:25], v[194:197], v[168:171], v[22:25]
	v_mfma_f32_16x16x32_bf16 v[26:29], v[198:201], v[168:171], v[26:29]
	v_mfma_f32_16x16x32_bf16 v[6:9], v[202:205], v[168:171], v[6:9]
	global_load_dwordx4 v[168:171], v176, s[14:15] offset:576
	s_waitcnt vmcnt(5)
	v_mfma_f32_16x16x32_bf16 v[34:37], v[182:185], v[172:175], v[34:37]
	global_load_dwordx4 v[182:185], v176, s[24:25] offset:576
	v_mfma_f32_16x16x32_bf16 v[38:41], v[186:189], v[172:175], v[38:41]
	global_load_dwordx4 v[186:189], v176, s[26:27] offset:576
	v_mfma_f32_16x16x32_bf16 v[42:45], v[190:193], v[172:175], v[42:45]
	global_load_dwordx4 v[190:193], v176, s[28:29] offset:576
	v_mfma_f32_16x16x32_bf16 v[46:49], v[194:197], v[172:175], v[46:49]
	global_load_dwordx4 v[194:197], v176, s[30:31] offset:576
	v_mfma_f32_16x16x32_bf16 v[50:53], v[198:201], v[172:175], v[50:53]
	global_load_dwordx4 v[198:201], v176, s[34:35] offset:576
	v_mfma_f32_16x16x32_bf16 v[30:33], v[202:205], v[172:175], v[30:33]
	global_load_dwordx4 v[202:205], v176, s[0:1] offset:576
	global_load_dwordx4 v[172:175], v176, s[16:17] offset:576
	s_waitcnt vmcnt(11)
	s_waitcnt vmcnt(6)
	v_mfma_f32_16x16x32_bf16 v[102:105], v[182:185], v[150:153], v[102:105]
	s_waitcnt vmcnt(5)
	v_mfma_f32_16x16x32_bf16 v[138:141], v[186:189], v[150:153], v[138:141]
	s_waitcnt vmcnt(4)
	v_mfma_f32_16x16x32_bf16 v[134:137], v[190:193], v[150:153], v[134:137]
	s_waitcnt vmcnt(3)
	v_mfma_f32_16x16x32_bf16 v[126:129], v[194:197], v[150:153], v[126:129]
	s_waitcnt vmcnt(2)
	v_mfma_f32_16x16x32_bf16 v[122:125], v[198:201], v[150:153], v[122:125]
	s_waitcnt vmcnt(1)
	v_mfma_f32_16x16x32_bf16 v[118:121], v[202:205], v[150:153], v[118:121]
	global_load_dwordx4 v[150:153], v176, s[6:7] offset:640
	v_mfma_f32_16x16x32_bf16 v[146:149], v[182:185], v[154:157], v[146:149]
	v_mfma_f32_16x16x32_bf16 v[142:145], v[186:189], v[154:157], v[142:145]
	v_mfma_f32_16x16x32_bf16 v[130:133], v[190:193], v[154:157], v[130:133]
	v_mfma_f32_16x16x32_bf16 v[114:117], v[194:197], v[154:157], v[114:117]
	v_mfma_f32_16x16x32_bf16 v[110:113], v[198:201], v[154:157], v[110:113]
	v_mfma_f32_16x16x32_bf16 v[106:109], v[202:205], v[154:157], v[106:109]
	global_load_dwordx4 v[154:157], v176, s[8:9] offset:640
	v_mfma_f32_16x16x32_bf16 v[94:97], v[182:185], v[158:161], v[94:97]
	v_mfma_f32_16x16x32_bf16 v[86:89], v[186:189], v[158:161], v[86:89]
	v_mfma_f32_16x16x32_bf16 v[78:81], v[190:193], v[158:161], v[78:81]
	v_mfma_f32_16x16x32_bf16 v[70:73], v[194:197], v[158:161], v[70:73]
	v_mfma_f32_16x16x32_bf16 v[62:65], v[198:201], v[158:161], v[62:65]
	v_mfma_f32_16x16x32_bf16 v[54:57], v[202:205], v[158:161], v[54:57]
	global_load_dwordx4 v[158:161], v176, s[10:11] offset:640
	v_mfma_f32_16x16x32_bf16 v[98:101], v[182:185], v[162:165], v[98:101]
	v_mfma_f32_16x16x32_bf16 v[90:93], v[186:189], v[162:165], v[90:93]
	v_mfma_f32_16x16x32_bf16 v[82:85], v[190:193], v[162:165], v[82:85]
	v_mfma_f32_16x16x32_bf16 v[74:77], v[194:197], v[162:165], v[74:77]
	v_mfma_f32_16x16x32_bf16 v[66:69], v[198:201], v[162:165], v[66:69]
	v_mfma_f32_16x16x32_bf16 v[58:61], v[202:205], v[162:165], v[58:61]
	global_load_dwordx4 v[162:165], v176, s[12:13] offset:640
	v_mfma_f32_16x16x32_bf16 v[10:13], v[182:185], v[168:171], v[10:13]
	v_mfma_f32_16x16x32_bf16 v[14:17], v[186:189], v[168:171], v[14:17]
	v_mfma_f32_16x16x32_bf16 v[18:21], v[190:193], v[168:171], v[18:21]
	v_mfma_f32_16x16x32_bf16 v[22:25], v[194:197], v[168:171], v[22:25]
	v_mfma_f32_16x16x32_bf16 v[26:29], v[198:201], v[168:171], v[26:29]
	v_mfma_f32_16x16x32_bf16 v[6:9], v[202:205], v[168:171], v[6:9]
	global_load_dwordx4 v[168:171], v176, s[14:15] offset:640
	s_waitcnt vmcnt(5)
	v_mfma_f32_16x16x32_bf16 v[34:37], v[182:185], v[172:175], v[34:37]
	global_load_dwordx4 v[182:185], v176, s[24:25] offset:640
	v_mfma_f32_16x16x32_bf16 v[38:41], v[186:189], v[172:175], v[38:41]
	global_load_dwordx4 v[186:189], v176, s[26:27] offset:640
	v_mfma_f32_16x16x32_bf16 v[42:45], v[190:193], v[172:175], v[42:45]
	global_load_dwordx4 v[190:193], v176, s[28:29] offset:640
	v_mfma_f32_16x16x32_bf16 v[46:49], v[194:197], v[172:175], v[46:49]
	global_load_dwordx4 v[194:197], v176, s[30:31] offset:640
	v_mfma_f32_16x16x32_bf16 v[50:53], v[198:201], v[172:175], v[50:53]
	global_load_dwordx4 v[198:201], v176, s[34:35] offset:640
	v_mfma_f32_16x16x32_bf16 v[30:33], v[202:205], v[172:175], v[30:33]
	global_load_dwordx4 v[202:205], v176, s[0:1] offset:640
	global_load_dwordx4 v[172:175], v176, s[16:17] offset:640
	s_waitcnt vmcnt(11)
	s_waitcnt vmcnt(6)
	v_mfma_f32_16x16x32_bf16 v[102:105], v[182:185], v[150:153], v[102:105]
	s_waitcnt vmcnt(5)
	v_mfma_f32_16x16x32_bf16 v[138:141], v[186:189], v[150:153], v[138:141]
	s_waitcnt vmcnt(4)
	v_mfma_f32_16x16x32_bf16 v[134:137], v[190:193], v[150:153], v[134:137]
	s_waitcnt vmcnt(3)
	v_mfma_f32_16x16x32_bf16 v[126:129], v[194:197], v[150:153], v[126:129]
	s_waitcnt vmcnt(2)
	v_mfma_f32_16x16x32_bf16 v[122:125], v[198:201], v[150:153], v[122:125]
	s_waitcnt vmcnt(1)
	v_mfma_f32_16x16x32_bf16 v[118:121], v[202:205], v[150:153], v[118:121]
	global_load_dwordx4 v[150:153], v176, s[6:7] offset:704
	v_mfma_f32_16x16x32_bf16 v[146:149], v[182:185], v[154:157], v[146:149]
	v_mfma_f32_16x16x32_bf16 v[142:145], v[186:189], v[154:157], v[142:145]
	v_mfma_f32_16x16x32_bf16 v[130:133], v[190:193], v[154:157], v[130:133]
	v_mfma_f32_16x16x32_bf16 v[114:117], v[194:197], v[154:157], v[114:117]
	v_mfma_f32_16x16x32_bf16 v[110:113], v[198:201], v[154:157], v[110:113]
	v_mfma_f32_16x16x32_bf16 v[106:109], v[202:205], v[154:157], v[106:109]
	global_load_dwordx4 v[154:157], v176, s[8:9] offset:704
	v_mfma_f32_16x16x32_bf16 v[94:97], v[182:185], v[158:161], v[94:97]
	v_mfma_f32_16x16x32_bf16 v[86:89], v[186:189], v[158:161], v[86:89]
	v_mfma_f32_16x16x32_bf16 v[78:81], v[190:193], v[158:161], v[78:81]
	v_mfma_f32_16x16x32_bf16 v[70:73], v[194:197], v[158:161], v[70:73]
	v_mfma_f32_16x16x32_bf16 v[62:65], v[198:201], v[158:161], v[62:65]
	v_mfma_f32_16x16x32_bf16 v[54:57], v[202:205], v[158:161], v[54:57]
	global_load_dwordx4 v[158:161], v176, s[10:11] offset:704
	v_mfma_f32_16x16x32_bf16 v[98:101], v[182:185], v[162:165], v[98:101]
	v_mfma_f32_16x16x32_bf16 v[90:93], v[186:189], v[162:165], v[90:93]
	v_mfma_f32_16x16x32_bf16 v[82:85], v[190:193], v[162:165], v[82:85]
	v_mfma_f32_16x16x32_bf16 v[74:77], v[194:197], v[162:165], v[74:77]
	v_mfma_f32_16x16x32_bf16 v[66:69], v[198:201], v[162:165], v[66:69]
	v_mfma_f32_16x16x32_bf16 v[58:61], v[202:205], v[162:165], v[58:61]
	global_load_dwordx4 v[162:165], v176, s[12:13] offset:704
	v_mfma_f32_16x16x32_bf16 v[10:13], v[182:185], v[168:171], v[10:13]
	v_mfma_f32_16x16x32_bf16 v[14:17], v[186:189], v[168:171], v[14:17]
	v_mfma_f32_16x16x32_bf16 v[18:21], v[190:193], v[168:171], v[18:21]
	v_mfma_f32_16x16x32_bf16 v[22:25], v[194:197], v[168:171], v[22:25]
	v_mfma_f32_16x16x32_bf16 v[26:29], v[198:201], v[168:171], v[26:29]
	v_mfma_f32_16x16x32_bf16 v[6:9], v[202:205], v[168:171], v[6:9]
	global_load_dwordx4 v[168:171], v176, s[14:15] offset:704
	s_waitcnt vmcnt(5)
	v_mfma_f32_16x16x32_bf16 v[34:37], v[182:185], v[172:175], v[34:37]
	global_load_dwordx4 v[182:185], v176, s[24:25] offset:704
	v_mfma_f32_16x16x32_bf16 v[38:41], v[186:189], v[172:175], v[38:41]
	global_load_dwordx4 v[186:189], v176, s[26:27] offset:704
	v_mfma_f32_16x16x32_bf16 v[42:45], v[190:193], v[172:175], v[42:45]
	global_load_dwordx4 v[190:193], v176, s[28:29] offset:704
	v_mfma_f32_16x16x32_bf16 v[46:49], v[194:197], v[172:175], v[46:49]
	global_load_dwordx4 v[194:197], v176, s[30:31] offset:704
	v_mfma_f32_16x16x32_bf16 v[50:53], v[198:201], v[172:175], v[50:53]
	global_load_dwordx4 v[198:201], v176, s[34:35] offset:704
	v_mfma_f32_16x16x32_bf16 v[30:33], v[202:205], v[172:175], v[30:33]
	global_load_dwordx4 v[202:205], v176, s[0:1] offset:704
	global_load_dwordx4 v[172:175], v176, s[16:17] offset:704
	s_waitcnt vmcnt(11)
	s_waitcnt vmcnt(6)
	v_mfma_f32_16x16x32_bf16 v[102:105], v[182:185], v[150:153], v[102:105]
	s_waitcnt vmcnt(5)
	v_mfma_f32_16x16x32_bf16 v[138:141], v[186:189], v[150:153], v[138:141]
	s_waitcnt vmcnt(4)
	v_mfma_f32_16x16x32_bf16 v[134:137], v[190:193], v[150:153], v[134:137]
	s_waitcnt vmcnt(3)
	v_mfma_f32_16x16x32_bf16 v[126:129], v[194:197], v[150:153], v[126:129]
	s_waitcnt vmcnt(2)
	v_mfma_f32_16x16x32_bf16 v[122:125], v[198:201], v[150:153], v[122:125]
	s_waitcnt vmcnt(1)
	v_mfma_f32_16x16x32_bf16 v[118:121], v[202:205], v[150:153], v[118:121]
	global_load_dwordx4 v[150:153], v176, s[6:7] offset:768
	v_mfma_f32_16x16x32_bf16 v[146:149], v[182:185], v[154:157], v[146:149]
	v_mfma_f32_16x16x32_bf16 v[142:145], v[186:189], v[154:157], v[142:145]
	v_mfma_f32_16x16x32_bf16 v[130:133], v[190:193], v[154:157], v[130:133]
	v_mfma_f32_16x16x32_bf16 v[114:117], v[194:197], v[154:157], v[114:117]
	v_mfma_f32_16x16x32_bf16 v[110:113], v[198:201], v[154:157], v[110:113]
	v_mfma_f32_16x16x32_bf16 v[106:109], v[202:205], v[154:157], v[106:109]
	global_load_dwordx4 v[154:157], v176, s[8:9] offset:768
	v_mfma_f32_16x16x32_bf16 v[94:97], v[182:185], v[158:161], v[94:97]
	v_mfma_f32_16x16x32_bf16 v[86:89], v[186:189], v[158:161], v[86:89]
	v_mfma_f32_16x16x32_bf16 v[78:81], v[190:193], v[158:161], v[78:81]
	v_mfma_f32_16x16x32_bf16 v[70:73], v[194:197], v[158:161], v[70:73]
	v_mfma_f32_16x16x32_bf16 v[62:65], v[198:201], v[158:161], v[62:65]
	v_mfma_f32_16x16x32_bf16 v[54:57], v[202:205], v[158:161], v[54:57]
	global_load_dwordx4 v[158:161], v176, s[10:11] offset:768
	v_mfma_f32_16x16x32_bf16 v[98:101], v[182:185], v[162:165], v[98:101]
	v_mfma_f32_16x16x32_bf16 v[90:93], v[186:189], v[162:165], v[90:93]
	v_mfma_f32_16x16x32_bf16 v[82:85], v[190:193], v[162:165], v[82:85]
	v_mfma_f32_16x16x32_bf16 v[74:77], v[194:197], v[162:165], v[74:77]
	v_mfma_f32_16x16x32_bf16 v[66:69], v[198:201], v[162:165], v[66:69]
	v_mfma_f32_16x16x32_bf16 v[58:61], v[202:205], v[162:165], v[58:61]
	global_load_dwordx4 v[162:165], v176, s[12:13] offset:768
	v_mfma_f32_16x16x32_bf16 v[10:13], v[182:185], v[168:171], v[10:13]
	v_mfma_f32_16x16x32_bf16 v[14:17], v[186:189], v[168:171], v[14:17]
	v_mfma_f32_16x16x32_bf16 v[18:21], v[190:193], v[168:171], v[18:21]
	v_mfma_f32_16x16x32_bf16 v[22:25], v[194:197], v[168:171], v[22:25]
	v_mfma_f32_16x16x32_bf16 v[26:29], v[198:201], v[168:171], v[26:29]
	v_mfma_f32_16x16x32_bf16 v[6:9], v[202:205], v[168:171], v[6:9]
	global_load_dwordx4 v[168:171], v176, s[14:15] offset:768
	s_waitcnt vmcnt(5)
	v_mfma_f32_16x16x32_bf16 v[34:37], v[182:185], v[172:175], v[34:37]
	global_load_dwordx4 v[182:185], v176, s[24:25] offset:768
	v_mfma_f32_16x16x32_bf16 v[38:41], v[186:189], v[172:175], v[38:41]
	global_load_dwordx4 v[186:189], v176, s[26:27] offset:768
	v_mfma_f32_16x16x32_bf16 v[42:45], v[190:193], v[172:175], v[42:45]
	global_load_dwordx4 v[190:193], v176, s[28:29] offset:768
	v_mfma_f32_16x16x32_bf16 v[46:49], v[194:197], v[172:175], v[46:49]
	global_load_dwordx4 v[194:197], v176, s[30:31] offset:768
	v_mfma_f32_16x16x32_bf16 v[50:53], v[198:201], v[172:175], v[50:53]
	global_load_dwordx4 v[198:201], v176, s[34:35] offset:768
	v_mfma_f32_16x16x32_bf16 v[30:33], v[202:205], v[172:175], v[30:33]
	global_load_dwordx4 v[202:205], v176, s[0:1] offset:768
	global_load_dwordx4 v[172:175], v176, s[16:17] offset:768
	s_waitcnt vmcnt(11)
	s_waitcnt vmcnt(6)
	v_mfma_f32_16x16x32_bf16 v[102:105], v[182:185], v[150:153], v[102:105]
	s_waitcnt vmcnt(5)
	v_mfma_f32_16x16x32_bf16 v[138:141], v[186:189], v[150:153], v[138:141]
	s_waitcnt vmcnt(4)
	v_mfma_f32_16x16x32_bf16 v[134:137], v[190:193], v[150:153], v[134:137]
	s_waitcnt vmcnt(3)
	v_mfma_f32_16x16x32_bf16 v[126:129], v[194:197], v[150:153], v[126:129]
	s_waitcnt vmcnt(2)
	v_mfma_f32_16x16x32_bf16 v[122:125], v[198:201], v[150:153], v[122:125]
	s_waitcnt vmcnt(1)
	v_mfma_f32_16x16x32_bf16 v[118:121], v[202:205], v[150:153], v[118:121]
	global_load_dwordx4 v[150:153], v176, s[6:7] offset:832
	v_mfma_f32_16x16x32_bf16 v[146:149], v[182:185], v[154:157], v[146:149]
	v_mfma_f32_16x16x32_bf16 v[142:145], v[186:189], v[154:157], v[142:145]
	v_mfma_f32_16x16x32_bf16 v[130:133], v[190:193], v[154:157], v[130:133]
	v_mfma_f32_16x16x32_bf16 v[114:117], v[194:197], v[154:157], v[114:117]
	v_mfma_f32_16x16x32_bf16 v[110:113], v[198:201], v[154:157], v[110:113]
	v_mfma_f32_16x16x32_bf16 v[106:109], v[202:205], v[154:157], v[106:109]
	global_load_dwordx4 v[154:157], v176, s[8:9] offset:832
	v_mfma_f32_16x16x32_bf16 v[94:97], v[182:185], v[158:161], v[94:97]
	v_mfma_f32_16x16x32_bf16 v[86:89], v[186:189], v[158:161], v[86:89]
	v_mfma_f32_16x16x32_bf16 v[78:81], v[190:193], v[158:161], v[78:81]
	v_mfma_f32_16x16x32_bf16 v[70:73], v[194:197], v[158:161], v[70:73]
	v_mfma_f32_16x16x32_bf16 v[62:65], v[198:201], v[158:161], v[62:65]
	v_mfma_f32_16x16x32_bf16 v[54:57], v[202:205], v[158:161], v[54:57]
	global_load_dwordx4 v[158:161], v176, s[10:11] offset:832
	v_mfma_f32_16x16x32_bf16 v[98:101], v[182:185], v[162:165], v[98:101]
	v_mfma_f32_16x16x32_bf16 v[90:93], v[186:189], v[162:165], v[90:93]
	v_mfma_f32_16x16x32_bf16 v[82:85], v[190:193], v[162:165], v[82:85]
	v_mfma_f32_16x16x32_bf16 v[74:77], v[194:197], v[162:165], v[74:77]
	v_mfma_f32_16x16x32_bf16 v[66:69], v[198:201], v[162:165], v[66:69]
	v_mfma_f32_16x16x32_bf16 v[58:61], v[202:205], v[162:165], v[58:61]
	global_load_dwordx4 v[162:165], v176, s[12:13] offset:832
	v_mfma_f32_16x16x32_bf16 v[10:13], v[182:185], v[168:171], v[10:13]
	v_mfma_f32_16x16x32_bf16 v[14:17], v[186:189], v[168:171], v[14:17]
	v_mfma_f32_16x16x32_bf16 v[18:21], v[190:193], v[168:171], v[18:21]
	v_mfma_f32_16x16x32_bf16 v[22:25], v[194:197], v[168:171], v[22:25]
	v_mfma_f32_16x16x32_bf16 v[26:29], v[198:201], v[168:171], v[26:29]
	v_mfma_f32_16x16x32_bf16 v[6:9], v[202:205], v[168:171], v[6:9]
	global_load_dwordx4 v[168:171], v176, s[14:15] offset:832
	s_waitcnt vmcnt(5)
	v_mfma_f32_16x16x32_bf16 v[34:37], v[182:185], v[172:175], v[34:37]
	global_load_dwordx4 v[182:185], v176, s[24:25] offset:832
	v_mfma_f32_16x16x32_bf16 v[38:41], v[186:189], v[172:175], v[38:41]
	global_load_dwordx4 v[186:189], v176, s[26:27] offset:832
	v_mfma_f32_16x16x32_bf16 v[42:45], v[190:193], v[172:175], v[42:45]
	global_load_dwordx4 v[190:193], v176, s[28:29] offset:832
	v_mfma_f32_16x16x32_bf16 v[46:49], v[194:197], v[172:175], v[46:49]
	global_load_dwordx4 v[194:197], v176, s[30:31] offset:832
	v_mfma_f32_16x16x32_bf16 v[50:53], v[198:201], v[172:175], v[50:53]
	global_load_dwordx4 v[198:201], v176, s[34:35] offset:832
	v_mfma_f32_16x16x32_bf16 v[30:33], v[202:205], v[172:175], v[30:33]
	global_load_dwordx4 v[202:205], v176, s[0:1] offset:832
	global_load_dwordx4 v[172:175], v176, s[16:17] offset:832
	s_waitcnt vmcnt(11)
	s_waitcnt vmcnt(6)
	v_mfma_f32_16x16x32_bf16 v[102:105], v[182:185], v[150:153], v[102:105]
	s_waitcnt vmcnt(5)
	v_mfma_f32_16x16x32_bf16 v[138:141], v[186:189], v[150:153], v[138:141]
	s_waitcnt vmcnt(4)
	v_mfma_f32_16x16x32_bf16 v[134:137], v[190:193], v[150:153], v[134:137]
	s_waitcnt vmcnt(3)
	v_mfma_f32_16x16x32_bf16 v[126:129], v[194:197], v[150:153], v[126:129]
	s_waitcnt vmcnt(2)
	v_mfma_f32_16x16x32_bf16 v[122:125], v[198:201], v[150:153], v[122:125]
	s_waitcnt vmcnt(1)
	v_mfma_f32_16x16x32_bf16 v[118:121], v[202:205], v[150:153], v[118:121]
	global_load_dwordx4 v[150:153], v176, s[6:7] offset:896
	v_mfma_f32_16x16x32_bf16 v[146:149], v[182:185], v[154:157], v[146:149]
	v_mfma_f32_16x16x32_bf16 v[142:145], v[186:189], v[154:157], v[142:145]
	v_mfma_f32_16x16x32_bf16 v[130:133], v[190:193], v[154:157], v[130:133]
	v_mfma_f32_16x16x32_bf16 v[114:117], v[194:197], v[154:157], v[114:117]
	v_mfma_f32_16x16x32_bf16 v[110:113], v[198:201], v[154:157], v[110:113]
	v_mfma_f32_16x16x32_bf16 v[106:109], v[202:205], v[154:157], v[106:109]
	global_load_dwordx4 v[154:157], v176, s[8:9] offset:896
	v_mfma_f32_16x16x32_bf16 v[94:97], v[182:185], v[158:161], v[94:97]
	v_mfma_f32_16x16x32_bf16 v[86:89], v[186:189], v[158:161], v[86:89]
	v_mfma_f32_16x16x32_bf16 v[78:81], v[190:193], v[158:161], v[78:81]
	v_mfma_f32_16x16x32_bf16 v[70:73], v[194:197], v[158:161], v[70:73]
	v_mfma_f32_16x16x32_bf16 v[62:65], v[198:201], v[158:161], v[62:65]
	v_mfma_f32_16x16x32_bf16 v[54:57], v[202:205], v[158:161], v[54:57]
	global_load_dwordx4 v[158:161], v176, s[10:11] offset:896
	v_mfma_f32_16x16x32_bf16 v[98:101], v[182:185], v[162:165], v[98:101]
	v_mfma_f32_16x16x32_bf16 v[90:93], v[186:189], v[162:165], v[90:93]
	v_mfma_f32_16x16x32_bf16 v[82:85], v[190:193], v[162:165], v[82:85]
	v_mfma_f32_16x16x32_bf16 v[74:77], v[194:197], v[162:165], v[74:77]
	v_mfma_f32_16x16x32_bf16 v[66:69], v[198:201], v[162:165], v[66:69]
	v_mfma_f32_16x16x32_bf16 v[58:61], v[202:205], v[162:165], v[58:61]
	global_load_dwordx4 v[162:165], v176, s[12:13] offset:896
	v_mfma_f32_16x16x32_bf16 v[10:13], v[182:185], v[168:171], v[10:13]
	v_mfma_f32_16x16x32_bf16 v[14:17], v[186:189], v[168:171], v[14:17]
	v_mfma_f32_16x16x32_bf16 v[18:21], v[190:193], v[168:171], v[18:21]
	v_mfma_f32_16x16x32_bf16 v[22:25], v[194:197], v[168:171], v[22:25]
	v_mfma_f32_16x16x32_bf16 v[26:29], v[198:201], v[168:171], v[26:29]
	v_mfma_f32_16x16x32_bf16 v[6:9], v[202:205], v[168:171], v[6:9]
	global_load_dwordx4 v[168:171], v176, s[14:15] offset:896
	s_waitcnt vmcnt(5)
	v_mfma_f32_16x16x32_bf16 v[34:37], v[182:185], v[172:175], v[34:37]
	global_load_dwordx4 v[182:185], v176, s[24:25] offset:896
	v_mfma_f32_16x16x32_bf16 v[38:41], v[186:189], v[172:175], v[38:41]
	global_load_dwordx4 v[186:189], v176, s[26:27] offset:896
	v_mfma_f32_16x16x32_bf16 v[42:45], v[190:193], v[172:175], v[42:45]
	global_load_dwordx4 v[190:193], v176, s[28:29] offset:896
	v_mfma_f32_16x16x32_bf16 v[46:49], v[194:197], v[172:175], v[46:49]
	global_load_dwordx4 v[194:197], v176, s[30:31] offset:896
	v_mfma_f32_16x16x32_bf16 v[50:53], v[198:201], v[172:175], v[50:53]
	global_load_dwordx4 v[198:201], v176, s[34:35] offset:896
	v_mfma_f32_16x16x32_bf16 v[30:33], v[202:205], v[172:175], v[30:33]
	global_load_dwordx4 v[202:205], v176, s[0:1] offset:896
	global_load_dwordx4 v[172:175], v176, s[16:17] offset:896
	s_waitcnt vmcnt(11)
	s_waitcnt vmcnt(6)
	v_mfma_f32_16x16x32_bf16 v[102:105], v[182:185], v[150:153], v[102:105]
	s_waitcnt vmcnt(5)
	v_mfma_f32_16x16x32_bf16 v[138:141], v[186:189], v[150:153], v[138:141]
	s_waitcnt vmcnt(4)
	v_mfma_f32_16x16x32_bf16 v[134:137], v[190:193], v[150:153], v[134:137]
	s_waitcnt vmcnt(3)
	v_mfma_f32_16x16x32_bf16 v[126:129], v[194:197], v[150:153], v[126:129]
	s_waitcnt vmcnt(2)
	v_mfma_f32_16x16x32_bf16 v[122:125], v[198:201], v[150:153], v[122:125]
	s_waitcnt vmcnt(1)
	v_mfma_f32_16x16x32_bf16 v[118:121], v[202:205], v[150:153], v[118:121]
	global_load_dwordx4 v[150:153], v176, s[6:7] offset:960
	v_mfma_f32_16x16x32_bf16 v[146:149], v[182:185], v[154:157], v[146:149]
	v_mfma_f32_16x16x32_bf16 v[142:145], v[186:189], v[154:157], v[142:145]
	v_mfma_f32_16x16x32_bf16 v[130:133], v[190:193], v[154:157], v[130:133]
	v_mfma_f32_16x16x32_bf16 v[114:117], v[194:197], v[154:157], v[114:117]
	v_mfma_f32_16x16x32_bf16 v[110:113], v[198:201], v[154:157], v[110:113]
	v_mfma_f32_16x16x32_bf16 v[106:109], v[202:205], v[154:157], v[106:109]
	global_load_dwordx4 v[154:157], v176, s[8:9] offset:960
	v_mfma_f32_16x16x32_bf16 v[94:97], v[182:185], v[158:161], v[94:97]
	v_mfma_f32_16x16x32_bf16 v[86:89], v[186:189], v[158:161], v[86:89]
	v_mfma_f32_16x16x32_bf16 v[78:81], v[190:193], v[158:161], v[78:81]
	v_mfma_f32_16x16x32_bf16 v[70:73], v[194:197], v[158:161], v[70:73]
	v_mfma_f32_16x16x32_bf16 v[62:65], v[198:201], v[158:161], v[62:65]
	v_mfma_f32_16x16x32_bf16 v[54:57], v[202:205], v[158:161], v[54:57]
	global_load_dwordx4 v[158:161], v176, s[10:11] offset:960
	v_mfma_f32_16x16x32_bf16 v[98:101], v[182:185], v[162:165], v[98:101]
	v_mfma_f32_16x16x32_bf16 v[90:93], v[186:189], v[162:165], v[90:93]
	v_mfma_f32_16x16x32_bf16 v[82:85], v[190:193], v[162:165], v[82:85]
	v_mfma_f32_16x16x32_bf16 v[74:77], v[194:197], v[162:165], v[74:77]
	v_mfma_f32_16x16x32_bf16 v[66:69], v[198:201], v[162:165], v[66:69]
	v_mfma_f32_16x16x32_bf16 v[58:61], v[202:205], v[162:165], v[58:61]
	global_load_dwordx4 v[162:165], v176, s[12:13] offset:960
	v_mfma_f32_16x16x32_bf16 v[10:13], v[182:185], v[168:171], v[10:13]
	v_mfma_f32_16x16x32_bf16 v[14:17], v[186:189], v[168:171], v[14:17]
	v_mfma_f32_16x16x32_bf16 v[18:21], v[190:193], v[168:171], v[18:21]
	v_mfma_f32_16x16x32_bf16 v[22:25], v[194:197], v[168:171], v[22:25]
	v_mfma_f32_16x16x32_bf16 v[26:29], v[198:201], v[168:171], v[26:29]
	v_mfma_f32_16x16x32_bf16 v[6:9], v[202:205], v[168:171], v[6:9]
	global_load_dwordx4 v[168:171], v176, s[14:15] offset:960
	s_waitcnt vmcnt(5)
	v_mfma_f32_16x16x32_bf16 v[34:37], v[182:185], v[172:175], v[34:37]
	global_load_dwordx4 v[182:185], v176, s[24:25] offset:960
	v_mfma_f32_16x16x32_bf16 v[38:41], v[186:189], v[172:175], v[38:41]
	global_load_dwordx4 v[186:189], v176, s[26:27] offset:960
	v_mfma_f32_16x16x32_bf16 v[42:45], v[190:193], v[172:175], v[42:45]
	global_load_dwordx4 v[190:193], v176, s[28:29] offset:960
	v_mfma_f32_16x16x32_bf16 v[46:49], v[194:197], v[172:175], v[46:49]
	global_load_dwordx4 v[194:197], v176, s[30:31] offset:960
	v_mfma_f32_16x16x32_bf16 v[50:53], v[198:201], v[172:175], v[50:53]
	global_load_dwordx4 v[198:201], v176, s[34:35] offset:960
	v_mfma_f32_16x16x32_bf16 v[30:33], v[202:205], v[172:175], v[30:33]
	global_load_dwordx4 v[202:205], v176, s[0:1] offset:960
	global_load_dwordx4 v[172:175], v176, s[16:17] offset:960
	s_waitcnt vmcnt(11)
	s_waitcnt vmcnt(6)
	v_mfma_f32_16x16x32_bf16 v[102:105], v[182:185], v[150:153], v[102:105]
	s_waitcnt vmcnt(5)
	v_mfma_f32_16x16x32_bf16 v[138:141], v[186:189], v[150:153], v[138:141]
	s_waitcnt vmcnt(4)
	v_mfma_f32_16x16x32_bf16 v[134:137], v[190:193], v[150:153], v[134:137]
	s_waitcnt vmcnt(3)
	v_mfma_f32_16x16x32_bf16 v[126:129], v[194:197], v[150:153], v[126:129]
	s_waitcnt vmcnt(2)
	v_mfma_f32_16x16x32_bf16 v[122:125], v[198:201], v[150:153], v[122:125]
	s_waitcnt vmcnt(1)
	v_mfma_f32_16x16x32_bf16 v[118:121], v[202:205], v[150:153], v[118:121]
	v_mfma_f32_16x16x32_bf16 v[146:149], v[182:185], v[154:157], v[146:149]
	v_mfma_f32_16x16x32_bf16 v[142:145], v[186:189], v[154:157], v[142:145]
	v_mfma_f32_16x16x32_bf16 v[130:133], v[190:193], v[154:157], v[130:133]
	v_mfma_f32_16x16x32_bf16 v[114:117], v[194:197], v[154:157], v[114:117]
	v_mfma_f32_16x16x32_bf16 v[110:113], v[198:201], v[154:157], v[110:113]
	v_mfma_f32_16x16x32_bf16 v[106:109], v[202:205], v[154:157], v[106:109]
	v_mfma_f32_16x16x32_bf16 v[94:97], v[182:185], v[158:161], v[94:97]
	v_mfma_f32_16x16x32_bf16 v[86:89], v[186:189], v[158:161], v[86:89]
	v_mfma_f32_16x16x32_bf16 v[78:81], v[190:193], v[158:161], v[78:81]
	v_mfma_f32_16x16x32_bf16 v[70:73], v[194:197], v[158:161], v[70:73]
	v_mfma_f32_16x16x32_bf16 v[62:65], v[198:201], v[158:161], v[62:65]
	v_mfma_f32_16x16x32_bf16 v[54:57], v[202:205], v[158:161], v[54:57]
	v_mfma_f32_16x16x32_bf16 v[98:101], v[182:185], v[162:165], v[98:101]
	v_mfma_f32_16x16x32_bf16 v[90:93], v[186:189], v[162:165], v[90:93]
	v_mfma_f32_16x16x32_bf16 v[82:85], v[190:193], v[162:165], v[82:85]
	v_mfma_f32_16x16x32_bf16 v[74:77], v[194:197], v[162:165], v[74:77]
	v_mfma_f32_16x16x32_bf16 v[66:69], v[198:201], v[162:165], v[66:69]
	v_mfma_f32_16x16x32_bf16 v[58:61], v[202:205], v[162:165], v[58:61]
	v_mfma_f32_16x16x32_bf16 v[10:13], v[182:185], v[168:171], v[10:13]
	v_mfma_f32_16x16x32_bf16 v[14:17], v[186:189], v[168:171], v[14:17]
	v_mfma_f32_16x16x32_bf16 v[18:21], v[190:193], v[168:171], v[18:21]
	v_mfma_f32_16x16x32_bf16 v[22:25], v[194:197], v[168:171], v[22:25]
	v_mfma_f32_16x16x32_bf16 v[26:29], v[198:201], v[168:171], v[26:29]
	v_mfma_f32_16x16x32_bf16 v[6:9], v[202:205], v[168:171], v[6:9]
	s_waitcnt vmcnt(0)
	v_mfma_f32_16x16x32_bf16 v[34:37], v[182:185], v[172:175], v[34:37]
	v_mfma_f32_16x16x32_bf16 v[38:41], v[186:189], v[172:175], v[38:41]
	v_mfma_f32_16x16x32_bf16 v[42:45], v[190:193], v[172:175], v[42:45]
	v_mfma_f32_16x16x32_bf16 v[46:49], v[194:197], v[172:175], v[46:49]
	v_mfma_f32_16x16x32_bf16 v[50:53], v[198:201], v[172:175], v[50:53]
	v_mfma_f32_16x16x32_bf16 v[30:33], v[202:205], v[172:175], v[30:33]
	v_readlane_b32 s24, v254, 28
	v_readlane_b32 s25, v254, 29
	v_ashrrev_i32_e32 v150, 4, v180
	v_readlane_b32 s0, v254, 4
	s_mov_b32 s19, s25
	v_lshl_add_u32 v153, v150, 2, 0
	v_add_u32_e32 v152, s0, v150
	s_lshl_b64 s[0:1], s[18:19], 2
	s_add_u32 s14, s22, s0
	s_addc_u32 s15, s23, s1
	v_lshlrev_b32_e32 v150, 4, v5
	v_mov_b32_e32 v151, v4
	s_add_u32 s6, s22, 0x3d518000
	v_lshl_add_u64 v[150:151], s[22:23], 0, v[150:151]
	s_mov_b64 s[0:1], 0x49b9c000
	v_and_b32_e32 v2, 3, v181
	s_mulk_i32 s2, 0x60
	s_addc_u32 s7, s23, 0
	s_lshl_b32 s24, s70, 6
	v_lshl_add_u64 v[150:151], v[150:151], 0, s[0:1]
	s_lshl_b64 s[0:1], s[70:71], 19
	s_lshl_b64 s[8:9], s[70:71], 14
	s_lshl_b64 s[10:11], s[70:71], 21
	s_lshl_b64 s[12:13], s[70:71], 16
	v_lshl_or_b32 v3, v2, 2, s2
	s_add_u32 s2, s22, 0x3cc00000
	s_movk_i32 s19, 0x84
	v_lshlrev_b32_e32 v2, 2, v5
	s_addc_u32 s3, s23, 0
	s_mul_i32 s16, s70, 0x40c000
	v_mul_lo_u32 v3, v3, s19
	s_add_u32 s16, s22, s16
	v_add3_u32 v156, 0, v2, v3
	s_movk_i32 s22, 0x108
	ds_write2_b32 v156, v102, v146 offset1:16
	ds_write2_b32 v156, v103, v147 offset0:33 offset1:49
	ds_write2_b32 v156, v104, v148 offset0:66 offset1:82
	ds_write2_b32 v156, v105, v149 offset0:99 offset1:115
	v_mad_u32_u24 v148, v5, s22, v153
	v_add_u32_e32 v149, 0x800, v156
	v_add_u32_e32 v157, 0x1000, v156
	v_add_u32_e32 v158, 0x1800, v156
	v_add_u32_e32 v159, 0x2000, v156
	v_add_u32_e32 v160, 0x2800, v156
	v_add_u32_e32 v161, 0x800, v148
	ds_write2_b32 v149, v138, v142 offset0:16 offset1:32
	ds_write2_b32 v149, v139, v143 offset0:49 offset1:65
	ds_write2_b32 v149, v140, v144 offset0:82 offset1:98
	ds_write2_b32 v149, v141, v145 offset0:115 offset1:131
	ds_write2_b32 v157, v134, v130 offset0:32 offset1:48
	ds_write2_b32 v157, v135, v131 offset0:65 offset1:81
	ds_write2_b32 v157, v136, v132 offset0:98 offset1:114
	ds_write2_b32 v157, v137, v133 offset0:131 offset1:147
	ds_write2_b32 v158, v126, v114 offset0:48 offset1:64
	ds_write2_b32 v158, v127, v115 offset0:81 offset1:97
	ds_write2_b32 v158, v128, v116 offset0:114 offset1:130
	ds_write2_b32 v158, v129, v117 offset0:147 offset1:163
	ds_write2_b32 v159, v122, v110 offset0:64 offset1:80
	ds_write2_b32 v159, v123, v111 offset0:97 offset1:113
	ds_write2_b32 v159, v124, v112 offset0:130 offset1:146
	ds_write2_b32 v159, v125, v113 offset0:163 offset1:179
	ds_write2_b32 v160, v118, v106 offset0:80 offset1:96
	ds_write2_b32 v160, v119, v107 offset0:113 offset1:129
	ds_write2_b32 v160, v120, v108 offset0:146 offset1:162
	ds_write2_b32 v160, v121, v109 offset0:179 offset1:195
	s_waitcnt lgkmcnt(0)
	s_barrier
	ds_read2_b32 v[102:103], v161 offset0:16 offset1:49
	v_add_u32_e32 v162, 0x1800, v148
	v_mad_u32_u24 v145, v5, s19, v153
	ds_read_b32 v3, v145
	v_add_u32_e32 v163, 0x3800, v148
	s_waitcnt lgkmcnt(1)
	v_pk_add_f32 v[112:113], v[102:103], 0 op_sel_hi:[1,0]
	ds_read2_b32 v[102:103], v162 offset0:48 offset1:81
	v_add_u32_e32 v164, 0x4800, v148
	ds_read2_b32 v[116:117], v163 offset0:112 offset1:145
	v_add_u32_e32 v165, 0x6800, v148
	v_add_u32_e32 v166, 0x7a00, v148
	s_waitcnt lgkmcnt(1)
	v_pk_add_f32 v[114:115], v[102:103], 0 op_sel_hi:[1,0]
	ds_read_b32 v102, v145 offset:12672
	v_add_f32_e32 v3, 0, v3
	v_add_u32_e32 v167, 0x9c00, v148
	v_add_u32_e32 v168, 0xac00, v148
	v_add_u32_e32 v169, 0xcc00, v148
	s_waitcnt lgkmcnt(0)
	v_add_f32_e32 v3, v3, v102
	ds_read2_b32 v[118:119], v164 offset0:144 offset1:177
	ds_read_b32 v102, v145 offset:25344
	ds_read2_b32 v[120:121], v165 offset0:208 offset1:241
	v_add_u32_e32 v171, 0xdc00, v148
	v_add_u32_e32 v170, 0xf780, v148
	v_readlane_b32 s44, v253, 15
	s_waitcnt lgkmcnt(1)
	v_add_f32_e32 v3, v3, v102
	ds_read2_b32 v[122:123], v166 offset0:112 offset1:145
	ds_read_b32 v102, v145 offset:38016
	ds_read2_b32 v[124:125], v167 offset0:48 offset1:81
	v_lshl_or_b32 v154, s70, 4, v5
	v_mov_b32_e32 v155, v4
	v_readlane_b32 s46, v253, 17
	s_waitcnt lgkmcnt(1)
	v_add_f32_e32 v3, v3, v102
	ds_read2_b32 v[126:127], v168 offset0:80 offset1:113
	ds_read_b32 v102, v145 offset:50688
	ds_read2_b32 v[128:129], v169 offset0:144 offset1:177
	v_readlane_b32 s47, v253, 18
	v_mov_b32_e32 v183, 0x3ecc95a3
	s_addc_u32 s17, s23, 0
	s_waitcnt lgkmcnt(1)
	v_add_f32_e32 v3, v3, v102
	ds_read2_b32 v[130:131], v171 offset0:176 offset1:209
	ds_read_b32 v102, v145 offset:63360
	ds_read_b32 v132, v148 offset:65472
	ds_read_b32 v133, v170 offset:2244
	v_lshl_add_u64 v[110:111], v[154:155], 2, s[46:47]
	s_mov_b32 s23, 0x7f800000
	v_mov_b32_e32 v184, 0x7f800000
	s_waitcnt lgkmcnt(2)
	v_add_f32_e32 v3, v3, v102
	v_add_u32_e32 v102, 0x12900, v153
	v_mad_u32_u24 v173, v5, s19, v102
	ds_read_b32 v103, v173
	v_mad_u32_u24 v102, v5, s22, v102
	v_add_u32_e32 v174, 0x800, v102
	v_add_u32_e32 v175, 0x1800, v102
	v_add_u32_e32 v102, 0x15a80, v153
	v_mad_u32_u24 v176, v5, s19, v102
	s_waitcnt lgkmcnt(0)
	v_add_f32_e32 v3, v3, v103
	ds_read_b32 v103, v176
	v_mad_u32_u24 v102, v5, s22, v102
	v_ashrrev_i32_e32 v153, 31, v152
	v_add_u32_e32 v177, 0x800, v102
	v_add_u32_e32 v178, 0x1800, v102
	s_waitcnt lgkmcnt(0)
	v_add_f32_e32 v3, v3, v103
	v_lshl_add_u64 v[102:103], v[152:153], 2, s[14:15]
	s_mov_b64 s[14:15], 0x10000
	v_lshl_add_u64 v[108:109], v[102:103], 0, s[14:15]
	v_add_co_u32_e32 v102, vcc, s91, v102
	s_mov_b32 s15, 0xbfb8aa3b
	s_nop 0
	v_addc_co_u32_e32 v103, vcc, 0, v103, vcc
	global_load_dword v102, v[102:103], off
	s_mov_b32 s19, 0x3f2aaaab
	s_mov_b32 s22, 0x3f317218
	v_mov_b32_e32 v185, 0x7fc00000
	v_add_u32_e32 v172, 0x1800, v170
	s_mov_b32 s33, 0x33800000
	ds_read2_b32 v[134:135], v172 offset0:48 offset1:81
	ds_read2_b32 v[136:137], v174 offset0:16 offset1:49
	ds_read2_b32 v[138:139], v175 offset0:48 offset1:81
	v_pk_add_f32 v[112:113], v[112:113], v[116:117]
	v_pk_add_f32 v[114:115], v[114:115], v[118:119]
	ds_read2_b32 v[140:141], v177 offset0:16 offset1:49
	ds_read2_b32 v[142:143], v178 offset0:48 offset1:81
	v_pk_add_f32 v[112:113], v[112:113], v[120:121]
	v_pk_add_f32 v[114:115], v[114:115], v[122:123]
	s_movk_i32 s14, 0x1fff
	v_pk_add_f32 v[112:113], v[112:113], v[124:125]
	v_pk_add_f32 v[114:115], v[114:115], v[126:127]
	v_add_u32_e32 v181, 0xffffe000, v152
	v_mov_b32_e32 v186, 0x1b100000
	v_pk_add_f32 v[112:113], v[112:113], v[128:129]
	v_pk_add_f32 v[114:115], v[114:115], v[130:131]
	v_pk_add_f32 v[112:113], v[112:113], v[132:133]
	s_waitcnt lgkmcnt(4)
	v_pk_add_f32 v[114:115], v[114:115], v[134:135]
	s_add_u32 s16, s16, 0x3cd00000
	s_waitcnt lgkmcnt(3)
	v_pk_add_f32 v[112:113], v[112:113], v[136:137]
	s_waitcnt lgkmcnt(2)
	v_pk_add_f32 v[114:115], v[114:115], v[138:139]
	s_addc_u32 s17, s17, 0
	s_waitcnt lgkmcnt(1)
	v_pk_add_f32 v[112:113], v[112:113], v[140:141]
	s_waitcnt lgkmcnt(0)
	v_pk_add_f32 v[114:115], v[114:115], v[142:143]
	v_readlane_b32 s48, v253, 19
	v_readlane_b32 s49, v253, 20
	v_readlane_b32 s51, v253, 22
	s_mov_b32 s51, 0x40c000
	s_mov_b32 s47, 0x120000
	s_mov_b64 s[48:49], 0x7ffff
	v_readlane_b32 s45, v253, 16
	v_readlane_b32 s50, v253, 21
	v_readlane_b32 s52, v253, 23
	v_readlane_b32 s53, v253, 24
	v_readlane_b32 s54, v253, 25
	v_readlane_b32 s55, v253, 26
	v_readlane_b32 s56, v253, 27
	v_readlane_b32 s57, v253, 28
	v_readlane_b32 s58, v253, 29
	v_readlane_b32 s59, v253, 30
	s_waitcnt vmcnt(0)
	v_fmamk_f32 v102, v102, 0x39800000, v246
	v_cmp_gt_f32_e32 vcc, s95, v102
	v_mul_f32_e32 v103, 0x4b800000, v102
	s_nop 0
	v_cndmask_b32_e32 v102, v102, v103, vcc
	v_rsq_f32_e32 v102, v102
	s_nop 0
	v_mul_f32_e32 v103, 0x45800000, v102
	v_cndmask_b32_e32 v144, v102, v103, vcc
	global_load_dword v102, v[110:111], off
	v_pk_mul_f32 v[116:117], v[112:113], v[144:145] op_sel_hi:[1,0]
	v_pk_mul_f32 v[112:113], v[114:115], v[144:145] op_sel_hi:[1,0]
	v_mov_b32_e32 v118, v117
	v_mov_b32_e32 v119, v113
	v_mov_b32_e32 v114, v116
	v_mov_b32_e32 v115, v112
	v_pk_mul_f32 v[118:119], v[118:119], v[118:119]
	s_waitcnt vmcnt(0)
	v_fmac_f32_e32 v102, v3, v144
	v_min_f32_e32 v3, 0, v102
	v_mul_f32_e64 v102, |v102|, s15
	v_exp_f32_e32 v104, v102
	v_pk_fma_f32 v[114:115], v[114:115], v[114:115], v[118:119]
	v_add_f32_e32 v105, 1.0, v104
	v_add_f32_e32 v102, -1.0, v105
	v_sub_f32_e32 v103, v102, v105
	v_add_f32_e32 v103, 1.0, v103
	v_sub_f32_e32 v102, v104, v102
	v_add_f32_e32 v106, v102, v103
	v_frexp_mant_f32_e32 v102, v105
	v_cmp_gt_f32_e32 vcc, s19, v102
	v_cvt_f64_f32_e32 v[102:103], v105
	v_frexp_exp_i32_f64_e32 v102, v[102:103]
	v_subbrev_co_u32_e32 v102, vcc, 0, v102, vcc
	v_sub_u32_e32 v103, 0, v102
	v_ldexp_f32 v105, v105, v103
	v_ldexp_f32 v103, v106, v103
	v_add_f32_e32 v106, -1.0, v105
	v_add_f32_e32 v107, 1.0, v106
	v_sub_f32_e32 v107, v105, v107
	v_add_f32_e32 v107, v103, v107
	v_add_f32_e32 v146, v106, v107
	v_sub_f32_e32 v106, v146, v106
	v_sub_f32_e32 v106, v107, v106
	v_add_f32_e32 v107, 1.0, v105
	v_add_f32_e32 v147, -1.0, v107
	v_sub_f32_e32 v105, v105, v147
	v_add_f32_e32 v103, v103, v105
	v_add_f32_e32 v105, v107, v103
	v_sub_f32_e32 v107, v105, v107
	v_sub_f32_e32 v103, v103, v107
	v_rcp_f32_e32 v107, v105
	v_cvt_f32_i32_e32 v102, v102
	v_cmp_neq_f32_e32 vcc, s23, v104
	v_add_f32_e32 v114, v114, v115
	v_mul_f32_e32 v147, v146, v107
	v_mul_f32_e32 v154, v105, v147
	v_fma_f32 v155, v147, v105, -v154
	v_fmac_f32_e32 v155, v147, v103
	v_add_f32_e32 v179, v154, v155
	v_sub_f32_e32 v180, v146, v179
	v_sub_f32_e32 v146, v146, v180
	v_sub_f32_e32 v154, v179, v154
	v_sub_f32_e32 v146, v146, v179
	v_add_f32_e32 v106, v106, v146
	v_sub_f32_e32 v146, v154, v155
	v_add_f32_e32 v106, v146, v106
	v_add_f32_e32 v146, v180, v106
	v_mul_f32_e32 v154, v107, v146
	v_mul_f32_e32 v155, v105, v154
	v_fma_f32 v105, v154, v105, -v155
	v_fmac_f32_e32 v105, v154, v103
	v_sub_f32_e32 v103, v180, v146
	v_add_f32_e32 v103, v106, v103
	v_add_f32_e32 v106, v155, v105
	v_sub_f32_e32 v179, v146, v106
	v_sub_f32_e32 v146, v146, v179
	v_sub_f32_e32 v155, v106, v155
	v_sub_f32_e32 v106, v146, v106
	v_add_f32_e32 v103, v103, v106
	v_sub_f32_e32 v105, v155, v105
	v_add_f32_e32 v103, v105, v103
	v_add_f32_e32 v105, v147, v154
	v_add_f32_e32 v103, v179, v103
	v_sub_f32_e32 v106, v105, v147
	v_mul_f32_e32 v103, v107, v103
	v_sub_f32_e32 v106, v154, v106
	v_add_f32_e32 v103, v106, v103
	v_mul_f32_e32 v147, 0x3f317218, v102
	v_add_f32_e32 v106, v105, v103
	v_fma_f32 v154, v102, s22, -v147
	v_mul_f32_e32 v107, v106, v106
	v_fmac_f32_e32 v154, 0xb102e308, v102
	v_sub_f32_e32 v102, v106, v105
	v_fmamk_f32 v146, v107, 0x3e9b6dac, v183
	v_sub_f32_e32 v102, v103, v102
	v_add_f32_e32 v103, v147, v154
	v_fmaak_f32 v146, v107, v146, 0x3f2aaada
	v_sub_f32_e32 v105, v103, v147
	v_ldexp_f32 v147, v106, 1
	v_mul_f32_e32 v106, v106, v107
	v_mul_f32_e32 v106, v106, v146
	v_add_f32_e32 v107, v147, v106
	v_sub_f32_e32 v146, v107, v147
	v_ldexp_f32 v102, v102, 1
	v_sub_f32_e32 v106, v106, v146
	v_add_f32_e32 v102, v102, v106
	v_add_f32_e32 v106, v107, v102
	v_sub_f32_e32 v107, v106, v107
	v_sub_f32_e32 v102, v102, v107
	v_add_f32_e32 v107, v103, v106
	v_sub_f32_e32 v146, v107, v103
	v_sub_f32_e32 v147, v107, v146
	v_sub_f32_e32 v105, v154, v105
	v_sub_f32_e32 v103, v103, v147
	v_sub_f32_e32 v106, v106, v146
	v_add_f32_e32 v103, v106, v103
	v_add_f32_e32 v106, v105, v102
	v_sub_f32_e32 v146, v106, v105
	v_sub_f32_e32 v147, v106, v146
	v_sub_f32_e32 v105, v105, v147
	v_sub_f32_e32 v102, v102, v146
	v_add_f32_e32 v103, v106, v103
	v_add_f32_e32 v102, v102, v105
	v_add_f32_e32 v105, v107, v103
	v_sub_f32_e32 v106, v105, v107
	v_sub_f32_e32 v103, v103, v106
	v_add_f32_e32 v102, v102, v103
	v_add_f32_e32 v102, v105, v102
	v_cndmask_b32_e32 v102, v184, v102, vcc
	v_cmp_ngt_f32_e32 vcc, -1.0, v104
	v_mov_b32_e32 v154, s1
	v_mov_b32_e32 v155, s9
	v_cndmask_b32_e32 v102, v185, v102, vcc
	v_cmp_neq_f32_e32 vcc, -1.0, v104
	v_mov_b32_e32 v179, s0
	v_mov_b32_e32 v180, s8
	v_cndmask_b32_e32 v102, v247, v102, vcc
	v_cmp_lt_f32_e64 vcc, |v104|, s33
	s_mov_b32 s1, s25
	v_writelane_b32 v254, s0, 28
	v_cndmask_b32_e32 v102, v102, v104, vcc
	v_sub_f32_e32 v106, v3, v102
	v_lshl_or_b32 v102, v152, 4, v5
	v_ashrrev_i32_e32 v103, 31, v102
	v_cmp_lt_i32_e32 vcc, s14, v152
	v_lshl_add_u64 v[102:103], v[102:103], 2, s[6:7]
	global_store_dword v[102:103], v106, off
	v_cndmask_b32_e32 v146, v152, v181, vcc
	v_cndmask_b32_e32 v102, v252, v186, vcc
	v_mov_b32_e32 v103, v4
	v_cndmask_b32_e32 v105, v154, v155, vcc
	v_cndmask_b32_e32 v104, v179, v180, vcc
	v_lshl_add_u64 v[102:103], s[82:83], 0, v[102:103]
	v_ashrrev_i32_e32 v147, 31, v146
	v_lshl_add_u64 v[102:103], v[102:103], 0, v[104:105]
	v_lshlrev_b64 v[104:105], 6, v[146:147]
	v_writelane_b32 v254, s1, 29
	s_lshl_b64 s[0:1], s[24:25], 2
	v_readlane_b32 s24, v253, 0
	v_lshl_add_u64 v[102:103], v[102:103], 0, v[104:105]
	v_mov_b32_e32 v3, v4
	v_readlane_b32 s26, v253, 2
	v_lshl_add_u64 v[102:103], v[102:103], 0, v[2:3]
	v_readlane_b32 s27, v253, 3
	s_add_u32 s8, s26, s0
	global_store_dword v[102:103], v106, off
	s_addc_u32 s9, s27, s1
	v_lshlrev_b32_e32 v106, 3, v5
	global_load_dwordx2 v[118:119], v106, s[8:9]
	ds_swizzle_b32 v115, v114 offset:swizzle(SWAP,1)
	v_and_b32_e32 v182, 15, v146
	v_or_b32_e32 v102, 0x800, v182
	v_and_b32_e32 v103, 0x7ff, v152
	v_cndmask_b32_e32 v102, v103, v102, vcc
	s_waitcnt lgkmcnt(0)
	v_add_f32_e32 v114, v114, v115
	ds_swizzle_b32 v115, v114 offset:swizzle(SWAP,2)
	v_lshlrev_b32_e32 v102, 8, v102
	v_mov_b32_e32 v103, v4
	v_lshl_add_u64 v[102:103], v[150:151], 0, v[102:103]
	global_load_dwordx4 v[102:105], v[102:103], off
	s_waitcnt lgkmcnt(0)
	v_add_f32_e32 v114, v114, v115
	ds_swizzle_b32 v115, v114 offset:swizzle(SWAP,4)
	v_mov_b32_e32 v107, v4
	v_cndmask_b32_e64 v121, v153, 0, vcc
	v_readlane_b32 s25, v253, 1
	v_readlane_b32 s28, v253, 4
	s_waitcnt lgkmcnt(0)
	v_add_f32_e32 v114, v114, v115
	ds_swizzle_b32 v115, v114 offset:swizzle(SWAP,8)
	v_readlane_b32 s29, v253, 5
	v_readlane_b32 s30, v253, 6
	v_readlane_b32 s31, v253, 7
	s_waitcnt lgkmcnt(0)
	v_add_f32_e32 v114, v114, v115
	v_fmamk_f32 v114, v114, 0x3c800000, v246
	v_cmp_gt_f32_e64 s[0:1], s95, v114
	v_mul_f32_e32 v115, 0x4b800000, v114
	s_nop 0
	v_cndmask_b32_e64 v114, v114, v115, s[0:1]
	v_rsq_f32_e32 v114, v114
	s_nop 0
	v_mul_f32_e32 v115, 0x45800000, v114
	v_cndmask_b32_e64 v114, v114, v115, s[0:1]
	s_movk_i32 s0, 0x1fdf
	s_waitcnt vmcnt(1)
	v_pk_mul_f32 v[118:119], v[118:119], v[114:115] op_sel_hi:[1,0]
	s_nop 0
	v_pk_mul_f32 v[116:117], v[116:117], v[118:119]
	global_load_dwordx2 v[118:119], v106, s[8:9] offset:128
	s_waitcnt vmcnt(0)
	v_pk_mul_f32 v[114:115], v[118:119], v[114:115] op_sel_hi:[1,0]
	s_nop 0
	v_pk_mul_f32 v[112:113], v[112:113], v[114:115]
	v_mov_b32_e32 v115, v104
	v_mov_b32_e32 v104, v103
	v_mov_b32_e32 v114, v102
	v_pk_mul_f32 v[102:103], v[104:105], v[112:113]
	s_nop 0
	v_pk_fma_f32 v[118:119], v[114:115], v[116:117], v[102:103] neg_lo:[0,0,1] neg_hi:[0,0,1]
	v_pk_mul_f32 v[102:103], v[104:105], v[116:117]
	v_mov_b32_e32 v104, s10
	v_pk_fma_f32 v[116:117], v[114:115], v[112:113], v[102:103]
	v_cndmask_b32_e32 v112, v250, v251, vcc
	v_mov_b32_e32 v113, v4
	v_mov_b32_e32 v102, s11
	v_mov_b32_e32 v103, s13
	v_mov_b32_e32 v105, s12
	v_cndmask_b32_e32 v115, v102, v103, vcc
	v_cndmask_b32_e32 v114, v104, v105, vcc
	v_lshl_add_u64 v[112:113], s[82:83], 0, v[112:113]
	v_lshl_add_u64 v[112:113], v[112:113], 0, v[114:115]
	v_lshlrev_b64 v[114:115], 8, v[146:147]
	v_lshl_add_u64 v[112:113], v[112:113], 0, v[114:115]
	v_lshl_add_u64 v[112:113], v[112:113], 0, v[106:107]
	global_store_dwordx2 v[112:113], v[118:119], off
	global_store_dwordx2 v[112:113], v[116:117], off offset:128
	v_lshrrev_b32_e32 v112, 4, v181
	s_movk_i32 s10, 0x810
	v_mul_lo_u32 v112, v112, s10
	v_or_b32_e32 v112, v112, v182
	v_add_u32_e32 v112, 0x800, v112
	v_cndmask_b32_e32 v120, v152, v112, vcc
	v_mov_b32_e32 v112, s3
	v_mov_b32_e32 v113, s17
	v_mov_b32_e32 v114, s2
	v_mov_b32_e32 v115, s16
	v_cndmask_b32_e32 v123, v112, v113, vcc
	v_cndmask_b32_e32 v122, v114, v115, vcc
	v_lshlrev_b64 v[120:121], 7, v[120:121]
	v_lshl_add_u64 v[120:121], v[122:123], 0, v[120:121]
	v_cvt_pk_bf16_f32 v122, v118, v119
	v_lshl_add_u64 v[118:119], v[120:121], 0, v[2:3]
	global_store_dword v[118:119], v122, off
	v_cvt_pk_bf16_f32 v116, v116, v117
	global_store_dword v[118:119], v116, off offset:64
	s_barrier
	ds_write2_b32 v156, v94, v98 offset1:16
	ds_write2_b32 v156, v95, v99 offset0:33 offset1:49
	ds_write2_b32 v156, v96, v100 offset0:66 offset1:82
	ds_write2_b32 v156, v97, v101 offset0:99 offset1:115
	ds_write2_b32 v149, v86, v90 offset0:16 offset1:32
	ds_write2_b32 v149, v87, v91 offset0:49 offset1:65
	ds_write2_b32 v149, v88, v92 offset0:82 offset1:98
	ds_write2_b32 v149, v89, v93 offset0:115 offset1:131
	ds_write2_b32 v157, v78, v82 offset0:32 offset1:48
	ds_write2_b32 v157, v79, v83 offset0:65 offset1:81
	ds_write2_b32 v157, v80, v84 offset0:98 offset1:114
	ds_write2_b32 v157, v81, v85 offset0:131 offset1:147
	ds_write2_b32 v158, v70, v74 offset0:48 offset1:64
	ds_write2_b32 v158, v71, v75 offset0:81 offset1:97
	ds_write2_b32 v158, v72, v76 offset0:114 offset1:130
	ds_write2_b32 v158, v73, v77 offset0:147 offset1:163
	ds_write2_b32 v159, v62, v66 offset0:64 offset1:80
	ds_write2_b32 v159, v63, v67 offset0:97 offset1:113
	ds_write2_b32 v159, v64, v68 offset0:130 offset1:146
	ds_write2_b32 v159, v65, v69 offset0:163 offset1:179
	ds_write2_b32 v160, v54, v58 offset0:80 offset1:96
	ds_write2_b32 v160, v55, v59 offset0:113 offset1:129
	ds_write2_b32 v160, v56, v60 offset0:146 offset1:162
	ds_write2_b32 v160, v57, v61 offset0:179 offset1:195
	s_waitcnt lgkmcnt(0)
	s_barrier
	ds_read_b32 v54, v145
	v_add_u32_e32 v93, 32, v152
	v_ashrrev_i32_e32 v94, 31, v93
	s_waitcnt lgkmcnt(0)
	v_add_f32_e32 v56, 0, v54
	ds_read2_b32 v[54:55], v161 offset0:16 offset1:49
	s_waitcnt lgkmcnt(0)
	v_pk_add_f32 v[58:59], v[54:55], 0 op_sel_hi:[1,0]
	ds_read2_b32 v[54:55], v162 offset0:48 offset1:81
	s_waitcnt lgkmcnt(0)
	v_pk_add_f32 v[60:61], v[54:55], 0 op_sel_hi:[1,0]
	ds_read_b32 v54, v145 offset:12672
	ds_read2_b32 v[64:65], v163 offset0:112 offset1:145
	ds_read2_b32 v[62:63], v164 offset0:144 offset1:177
	ds_read_b32 v55, v145 offset:25344
	s_waitcnt lgkmcnt(2)
	v_pk_add_f32 v[58:59], v[58:59], v[64:65]
	v_add_f32_e32 v54, v56, v54
	s_waitcnt lgkmcnt(0)
	v_add_f32_e32 v54, v54, v55
	ds_read2_b32 v[68:69], v165 offset0:208 offset1:241
	ds_read2_b32 v[66:67], v166 offset0:112 offset1:145
	ds_read_b32 v55, v145 offset:38016
	v_pk_add_f32 v[60:61], v[60:61], v[62:63]
	s_waitcnt lgkmcnt(2)
	v_pk_add_f32 v[58:59], v[58:59], v[68:69]
	s_waitcnt lgkmcnt(1)
	v_pk_add_f32 v[60:61], v[60:61], v[66:67]
	s_waitcnt lgkmcnt(0)
	v_add_f32_e32 v54, v54, v55
	ds_read2_b32 v[72:73], v167 offset0:48 offset1:81
	ds_read2_b32 v[70:71], v168 offset0:80 offset1:113
	ds_read_b32 v55, v145 offset:50688
	s_waitcnt lgkmcnt(2)
	v_pk_add_f32 v[58:59], v[58:59], v[72:73]
	s_waitcnt lgkmcnt(1)
	v_pk_add_f32 v[60:61], v[60:61], v[70:71]
	s_waitcnt lgkmcnt(0)
	v_add_f32_e32 v54, v54, v55
	ds_read2_b32 v[76:77], v169 offset0:144 offset1:177
	ds_read2_b32 v[74:75], v171 offset0:176 offset1:209
	ds_read_b32 v55, v145 offset:63360
	s_waitcnt lgkmcnt(2)
	v_pk_add_f32 v[58:59], v[58:59], v[76:77]
	s_waitcnt lgkmcnt(1)
	v_pk_add_f32 v[60:61], v[60:61], v[74:75]
	s_waitcnt lgkmcnt(0)
	v_add_f32_e32 v54, v54, v55
	ds_read_b32 v78, v148 offset:65472
	ds_read_b32 v79, v170 offset:2244
	ds_read2_b32 v[80:81], v172 offset0:48 offset1:81
	ds_read_b32 v55, v173
	s_waitcnt lgkmcnt(2)
	v_pk_add_f32 v[58:59], v[58:59], v[78:79]
	s_waitcnt lgkmcnt(1)
	v_pk_add_f32 v[60:61], v[60:61], v[80:81]
	s_waitcnt lgkmcnt(0)
	v_add_f32_e32 v54, v54, v55
	ds_read2_b32 v[84:85], v174 offset0:16 offset1:49
	ds_read2_b32 v[82:83], v175 offset0:48 offset1:81
	ds_read_b32 v55, v176
	ds_read2_b32 v[88:89], v177 offset0:16 offset1:49
	ds_read2_b32 v[86:87], v178 offset0:48 offset1:81
	s_waitcnt lgkmcnt(4)
	v_pk_add_f32 v[58:59], v[58:59], v[84:85]
	s_waitcnt lgkmcnt(3)
	v_pk_add_f32 v[60:61], v[60:61], v[82:83]
	s_waitcnt lgkmcnt(2)
	v_add_f32_e32 v54, v54, v55
	global_load_dword v55, v[108:109], off offset:128
	s_waitcnt lgkmcnt(1)
	v_pk_add_f32 v[58:59], v[58:59], v[88:89]
	s_waitcnt lgkmcnt(0)
	v_pk_add_f32 v[60:61], v[60:61], v[86:87]
	s_waitcnt vmcnt(0)
	v_fmamk_f32 v55, v55, 0x39800000, v246
	v_cmp_gt_f32_e32 vcc, s95, v55
	v_mul_f32_e32 v56, 0x4b800000, v55
	s_nop 0
	v_cndmask_b32_e32 v55, v55, v56, vcc
	v_rsq_f32_e32 v55, v55
	s_nop 0
	v_mul_f32_e32 v56, 0x45800000, v55
	v_cndmask_b32_e32 v92, v55, v56, vcc
	global_load_dword v55, v[110:111], off
	v_pk_mul_f32 v[62:63], v[58:59], v[92:93] op_sel_hi:[1,0]
	v_pk_mul_f32 v[58:59], v[60:61], v[92:93] op_sel_hi:[1,0]
	v_mov_b32_e32 v64, v63
	v_mov_b32_e32 v65, v59
	v_mov_b32_e32 v60, v62
	v_mov_b32_e32 v61, v58
	v_pk_mul_f32 v[64:65], v[64:65], v[64:65]
	s_waitcnt vmcnt(0)
	v_fmac_f32_e32 v55, v54, v92
	v_mul_f32_e64 v54, |v55|, s15
	v_exp_f32_e32 v57, v54
	v_min_f32_e32 v56, 0, v55
	v_pk_fma_f32 v[60:61], v[60:61], v[60:61], v[64:65]
	v_add_f32_e32 v90, 1.0, v57
	v_add_f32_e32 v54, -1.0, v90
	v_sub_f32_e32 v55, v54, v90
	v_add_f32_e32 v55, 1.0, v55
	v_sub_f32_e32 v54, v57, v54
	v_add_f32_e32 v91, v54, v55
	v_frexp_mant_f32_e32 v54, v90
	v_cmp_gt_f32_e32 vcc, s19, v54
	v_cvt_f64_f32_e32 v[54:55], v90
	v_frexp_exp_i32_f64_e32 v54, v[54:55]
	v_subbrev_co_u32_e32 v54, vcc, 0, v54, vcc
	v_sub_u32_e32 v55, 0, v54
	v_ldexp_f32 v90, v90, v55
	v_ldexp_f32 v55, v91, v55
	v_add_f32_e32 v91, -1.0, v90
	v_add_f32_e32 v95, 1.0, v91
	v_sub_f32_e32 v95, v90, v95
	v_add_f32_e32 v95, v55, v95
	v_add_f32_e32 v96, v91, v95
	v_sub_f32_e32 v91, v96, v91
	v_sub_f32_e32 v91, v95, v91
	v_add_f32_e32 v95, 1.0, v90
	v_add_f32_e32 v97, -1.0, v95
	v_sub_f32_e32 v90, v90, v97
	v_add_f32_e32 v55, v55, v90
	v_add_f32_e32 v90, v95, v55
	v_sub_f32_e32 v95, v90, v95
	v_sub_f32_e32 v55, v55, v95
	v_rcp_f32_e32 v95, v90
	v_cvt_f32_i32_e32 v54, v54
	v_cmp_neq_f32_e32 vcc, s23, v57
	v_add_f32_e32 v60, v60, v61
	v_mul_f32_e32 v97, v96, v95
	v_mul_f32_e32 v98, v90, v97
	v_fma_f32 v99, v97, v90, -v98
	v_fmac_f32_e32 v99, v97, v55
	v_add_f32_e32 v100, v98, v99
	v_sub_f32_e32 v101, v96, v100
	v_sub_f32_e32 v96, v96, v101
	v_sub_f32_e32 v98, v100, v98
	v_sub_f32_e32 v96, v96, v100
	v_add_f32_e32 v91, v91, v96
	v_sub_f32_e32 v96, v98, v99
	v_add_f32_e32 v91, v96, v91
	v_add_f32_e32 v96, v101, v91
	v_mul_f32_e32 v98, v95, v96
	v_mul_f32_e32 v99, v90, v98
	v_fma_f32 v90, v98, v90, -v99
	v_fmac_f32_e32 v90, v98, v55
	v_sub_f32_e32 v55, v101, v96
	v_add_f32_e32 v55, v91, v55
	v_add_f32_e32 v91, v99, v90
	v_sub_f32_e32 v100, v96, v91
	v_sub_f32_e32 v96, v96, v100
	v_sub_f32_e32 v99, v91, v99
	v_sub_f32_e32 v91, v96, v91
	v_add_f32_e32 v55, v55, v91
	v_sub_f32_e32 v90, v99, v90
	v_add_f32_e32 v55, v90, v55
	v_add_f32_e32 v90, v97, v98
	v_add_f32_e32 v55, v100, v55
	v_sub_f32_e32 v91, v90, v97
	v_mul_f32_e32 v55, v95, v55
	v_sub_f32_e32 v91, v98, v91
	v_add_f32_e32 v55, v91, v55
	v_mul_f32_e32 v97, 0x3f317218, v54
	v_add_f32_e32 v91, v90, v55
	v_fma_f32 v98, v54, s22, -v97
	v_mul_f32_e32 v95, v91, v91
	v_fmac_f32_e32 v98, 0xb102e308, v54
	v_sub_f32_e32 v54, v91, v90
	v_fmamk_f32 v96, v95, 0x3e9b6dac, v183
	v_sub_f32_e32 v54, v55, v54
	v_add_f32_e32 v55, v97, v98
	v_fmaak_f32 v96, v95, v96, 0x3f2aaada
	v_sub_f32_e32 v90, v55, v97
	v_ldexp_f32 v97, v91, 1
	v_mul_f32_e32 v91, v91, v95
	v_mul_f32_e32 v91, v91, v96
	v_add_f32_e32 v95, v97, v91
	v_sub_f32_e32 v96, v95, v97
	v_ldexp_f32 v54, v54, 1
	v_sub_f32_e32 v91, v91, v96
	v_add_f32_e32 v54, v54, v91
	v_add_f32_e32 v91, v95, v54
	v_sub_f32_e32 v95, v91, v95
	v_sub_f32_e32 v54, v54, v95
	v_add_f32_e32 v95, v55, v91
	v_sub_f32_e32 v96, v95, v55
	v_sub_f32_e32 v97, v95, v96
	v_sub_f32_e32 v90, v98, v90
	v_sub_f32_e32 v55, v55, v97
	v_sub_f32_e32 v91, v91, v96
	v_add_f32_e32 v55, v91, v55
	v_add_f32_e32 v91, v90, v54
	v_sub_f32_e32 v96, v91, v90
	v_sub_f32_e32 v97, v91, v96
	v_sub_f32_e32 v90, v90, v97
	v_sub_f32_e32 v54, v54, v96
	v_add_f32_e32 v55, v91, v55
	v_add_f32_e32 v54, v54, v90
	v_add_f32_e32 v90, v95, v55
	v_sub_f32_e32 v91, v90, v95
	v_sub_f32_e32 v55, v55, v91
	v_add_f32_e32 v54, v54, v55
	v_add_f32_e32 v54, v90, v54
	v_cndmask_b32_e32 v54, v184, v54, vcc
	v_cmp_ngt_f32_e32 vcc, -1.0, v57
	v_add_u32_e32 v95, 0xffffe020, v152
	ds_swizzle_b32 v61, v60 offset:swizzle(SWAP,1)
	v_cndmask_b32_e32 v54, v185, v54, vcc
	v_cmp_neq_f32_e32 vcc, -1.0, v57
	s_waitcnt lgkmcnt(0)
	v_add_f32_e32 v60, v60, v61
	v_cndmask_b32_e32 v54, v247, v54, vcc
	v_cmp_lt_f32_e64 vcc, |v57|, s33
	ds_swizzle_b32 v61, v60 offset:swizzle(SWAP,2)
	s_waitcnt lgkmcnt(0)
	v_add_f32_e32 v60, v60, v61
	v_cndmask_b32_e32 v54, v54, v57, vcc
	v_sub_f32_e32 v96, v56, v54
	v_lshl_or_b32 v54, v93, 4, v5
	v_ashrrev_i32_e32 v55, 31, v54
	v_cmp_lt_i32_e32 vcc, s0, v152
	v_lshl_add_u64 v[54:55], v[54:55], 2, s[6:7]
	global_store_dword v[54:55], v96, off
	v_cndmask_b32_e32 v90, v93, v95, vcc
	v_cndmask_b32_e32 v54, v252, v186, vcc
	v_mov_b32_e32 v55, v4
	v_cndmask_b32_e32 v57, v154, v155, vcc
	v_cndmask_b32_e32 v56, v179, v180, vcc
	v_lshl_add_u64 v[54:55], s[82:83], 0, v[54:55]
	v_ashrrev_i32_e32 v91, 31, v90
	v_lshl_add_u64 v[54:55], v[54:55], 0, v[56:57]
	v_lshlrev_b64 v[56:57], 6, v[90:91]
	v_lshl_add_u64 v[54:55], v[54:55], 0, v[56:57]
	v_lshl_add_u64 v[54:55], v[54:55], 0, v[2:3]
	global_store_dword v[54:55], v96, off
	global_load_dwordx2 v[64:65], v106, s[8:9]
	ds_swizzle_b32 v61, v60 offset:swizzle(SWAP,4)
	v_and_b32_e32 v96, 15, v90
	v_or_b32_e32 v54, 0x800, v96
	v_and_b32_e32 v55, 0x7ff, v93
	v_cndmask_b32_e32 v54, v55, v54, vcc
	s_waitcnt lgkmcnt(0)
	v_add_f32_e32 v60, v60, v61
	ds_swizzle_b32 v61, v60 offset:swizzle(SWAP,8)
	v_lshlrev_b32_e32 v54, 8, v54
	v_mov_b32_e32 v55, v4
	v_lshl_add_u64 v[54:55], v[150:151], 0, v[54:55]
	global_load_dwordx4 v[54:57], v[54:55], off
	s_waitcnt lgkmcnt(0)
	v_add_f32_e32 v60, v60, v61
	v_fmamk_f32 v60, v60, 0x3c800000, v246
	v_cmp_gt_f32_e64 s[0:1], s95, v60
	v_mul_f32_e32 v61, 0x4b800000, v60
	s_nop 0
	v_cndmask_b32_e64 v60, v60, v61, s[0:1]
	v_rsq_f32_e32 v60, v60
	s_nop 0
	v_mul_f32_e32 v61, 0x45800000, v60
	v_cndmask_b32_e64 v60, v60, v61, s[0:1]
	s_movk_i32 s0, 0x1fbf
	s_waitcnt vmcnt(1)
	v_pk_mul_f32 v[64:65], v[64:65], v[60:61] op_sel_hi:[1,0]
	s_nop 0
	v_pk_mul_f32 v[62:63], v[62:63], v[64:65]
	global_load_dwordx2 v[64:65], v106, s[8:9] offset:128
	s_waitcnt vmcnt(0)
	v_pk_mul_f32 v[60:61], v[64:65], v[60:61] op_sel_hi:[1,0]
	s_nop 0
	v_pk_mul_f32 v[58:59], v[58:59], v[60:61]
	v_mov_b32_e32 v61, v56
	v_mov_b32_e32 v56, v55
	v_mov_b32_e32 v60, v54
	v_pk_mul_f32 v[54:55], v[56:57], v[58:59]
	v_pk_mul_f32 v[56:57], v[56:57], v[62:63]
	v_pk_fma_f32 v[54:55], v[60:61], v[62:63], v[54:55] neg_lo:[0,0,1] neg_hi:[0,0,1]
	v_pk_fma_f32 v[56:57], v[60:61], v[58:59], v[56:57]
	v_cndmask_b32_e32 v58, v250, v251, vcc
	v_mov_b32_e32 v59, v4
	v_cndmask_b32_e32 v61, v102, v103, vcc
	v_cndmask_b32_e32 v60, v104, v105, vcc
	v_lshl_add_u64 v[58:59], s[82:83], 0, v[58:59]
	v_lshl_add_u64 v[58:59], v[58:59], 0, v[60:61]
	v_lshlrev_b64 v[60:61], 8, v[90:91]
	v_lshl_add_u64 v[58:59], v[58:59], 0, v[60:61]
	v_lshl_add_u64 v[58:59], v[58:59], 0, v[106:107]
	global_store_dwordx2 v[58:59], v[54:55], off
	global_store_dwordx2 v[58:59], v[56:57], off offset:128
	v_lshrrev_b32_e32 v58, 4, v95
	v_mul_lo_u32 v58, v58, s10
	v_or_b32_e32 v58, v58, v96
	v_add_u32_e32 v58, 0x800, v58
	v_cndmask_b32_e64 v59, v94, 0, vcc
	v_cndmask_b32_e32 v58, v93, v58, vcc
	v_cndmask_b32_e32 v61, v112, v113, vcc
	v_cndmask_b32_e32 v60, v114, v115, vcc
	v_lshlrev_b64 v[58:59], 7, v[58:59]
	v_lshl_add_u64 v[58:59], v[60:61], 0, v[58:59]
	v_cvt_pk_bf16_f32 v60, v54, v55
	v_lshl_add_u64 v[54:55], v[58:59], 0, v[2:3]
	global_store_dword v[54:55], v60, off
	v_cvt_pk_bf16_f32 v56, v56, v57
	global_store_dword v[54:55], v56, off offset:64
	s_barrier
	ds_write2_b32 v156, v10, v34 offset1:16
	ds_write2_b32 v156, v11, v35 offset0:33 offset1:49
	ds_write2_b32 v156, v12, v36 offset0:66 offset1:82
	ds_write2_b32 v156, v13, v37 offset0:99 offset1:115
	ds_write2_b32 v149, v14, v38 offset0:16 offset1:32
	ds_write2_b32 v149, v15, v39 offset0:49 offset1:65
	ds_write2_b32 v149, v16, v40 offset0:82 offset1:98
	ds_write2_b32 v149, v17, v41 offset0:115 offset1:131
	ds_write2_b32 v157, v18, v42 offset0:32 offset1:48
	ds_write2_b32 v157, v19, v43 offset0:65 offset1:81
	ds_write2_b32 v157, v20, v44 offset0:98 offset1:114
	ds_write2_b32 v157, v21, v45 offset0:131 offset1:147
	ds_write2_b32 v158, v22, v46 offset0:48 offset1:64
	ds_write2_b32 v158, v23, v47 offset0:81 offset1:97
	ds_write2_b32 v158, v24, v48 offset0:114 offset1:130
	ds_write2_b32 v158, v25, v49 offset0:147 offset1:163
	ds_write2_b32 v159, v26, v50 offset0:64 offset1:80
	ds_write2_b32 v159, v27, v51 offset0:97 offset1:113
	ds_write2_b32 v159, v28, v52 offset0:130 offset1:146
	ds_write2_b32 v159, v29, v53 offset0:163 offset1:179
	ds_write2_b32 v160, v6, v30 offset0:80 offset1:96
	ds_write2_b32 v160, v7, v31 offset0:113 offset1:129
	ds_write2_b32 v160, v8, v32 offset0:146 offset1:162
	ds_write2_b32 v160, v9, v33 offset0:179 offset1:195
	s_waitcnt lgkmcnt(0)
	s_barrier
	ds_read_b32 v6, v145
	v_add_u32_e32 v45, 64, v152
	v_ashrrev_i32_e32 v46, 31, v45
	s_waitcnt lgkmcnt(0)
	v_add_f32_e32 v8, 0, v6
	ds_read2_b32 v[6:7], v161 offset0:16 offset1:49
	s_waitcnt lgkmcnt(0)
	v_pk_add_f32 v[10:11], v[6:7], 0 op_sel_hi:[1,0]
	ds_read2_b32 v[6:7], v162 offset0:48 offset1:81
	s_waitcnt lgkmcnt(0)
	v_pk_add_f32 v[12:13], v[6:7], 0 op_sel_hi:[1,0]
	ds_read_b32 v6, v145 offset:12672
	ds_read2_b32 v[16:17], v163 offset0:112 offset1:145
	ds_read2_b32 v[14:15], v164 offset0:144 offset1:177
	ds_read_b32 v7, v145 offset:25344
	s_waitcnt lgkmcnt(2)
	v_pk_add_f32 v[10:11], v[10:11], v[16:17]
	v_add_f32_e32 v6, v8, v6
	s_waitcnt lgkmcnt(0)
	v_add_f32_e32 v6, v6, v7
	ds_read2_b32 v[20:21], v165 offset0:208 offset1:241
	ds_read2_b32 v[18:19], v166 offset0:112 offset1:145
	ds_read_b32 v7, v145 offset:38016
	v_pk_add_f32 v[12:13], v[12:13], v[14:15]
	s_waitcnt lgkmcnt(2)
	v_pk_add_f32 v[10:11], v[10:11], v[20:21]
	s_waitcnt lgkmcnt(1)
	v_pk_add_f32 v[12:13], v[12:13], v[18:19]
	s_waitcnt lgkmcnt(0)
	v_add_f32_e32 v6, v6, v7
	ds_read2_b32 v[24:25], v167 offset0:48 offset1:81
	ds_read2_b32 v[22:23], v168 offset0:80 offset1:113
	ds_read_b32 v7, v145 offset:50688
	s_waitcnt lgkmcnt(2)
	v_pk_add_f32 v[10:11], v[10:11], v[24:25]
	s_waitcnt lgkmcnt(1)
	v_pk_add_f32 v[12:13], v[12:13], v[22:23]
	s_waitcnt lgkmcnt(0)
	v_add_f32_e32 v6, v6, v7
	ds_read2_b32 v[28:29], v169 offset0:144 offset1:177
	ds_read2_b32 v[26:27], v171 offset0:176 offset1:209
	ds_read_b32 v7, v145 offset:63360
	s_waitcnt lgkmcnt(2)
	v_pk_add_f32 v[10:11], v[10:11], v[28:29]
	s_waitcnt lgkmcnt(1)
	v_pk_add_f32 v[12:13], v[12:13], v[26:27]
	s_waitcnt lgkmcnt(0)
	v_add_f32_e32 v6, v6, v7
	ds_read_b32 v30, v148 offset:65472
	ds_read_b32 v31, v170 offset:2244
	ds_read2_b32 v[32:33], v172 offset0:48 offset1:81
	ds_read_b32 v7, v173
	s_waitcnt lgkmcnt(2)
	v_pk_add_f32 v[10:11], v[10:11], v[30:31]
	s_waitcnt lgkmcnt(1)
	v_pk_add_f32 v[12:13], v[12:13], v[32:33]
	s_waitcnt lgkmcnt(0)
	v_add_f32_e32 v6, v6, v7
	ds_read2_b32 v[36:37], v174 offset0:16 offset1:49
	ds_read2_b32 v[34:35], v175 offset0:48 offset1:81
	ds_read_b32 v7, v176
	ds_read2_b32 v[40:41], v177 offset0:16 offset1:49
	ds_read2_b32 v[38:39], v178 offset0:48 offset1:81
	s_waitcnt lgkmcnt(4)
	v_pk_add_f32 v[10:11], v[10:11], v[36:37]
	s_waitcnt lgkmcnt(3)
	v_pk_add_f32 v[12:13], v[12:13], v[34:35]
	s_waitcnt lgkmcnt(2)
	v_add_f32_e32 v6, v6, v7
	global_load_dword v7, v[108:109], off offset:256
	s_waitcnt lgkmcnt(1)
	v_pk_add_f32 v[10:11], v[10:11], v[40:41]
	s_waitcnt lgkmcnt(0)
	v_pk_add_f32 v[12:13], v[12:13], v[38:39]
	s_waitcnt vmcnt(0)
	v_fmamk_f32 v7, v7, 0x39800000, v246
	v_cmp_gt_f32_e32 vcc, s95, v7
	v_mul_f32_e32 v8, 0x4b800000, v7
	s_nop 0
	v_cndmask_b32_e32 v7, v7, v8, vcc
	v_rsq_f32_e32 v7, v7
	s_nop 0
	v_mul_f32_e32 v8, 0x45800000, v7
	v_cndmask_b32_e32 v44, v7, v8, vcc
	global_load_dword v7, v[110:111], off
	v_pk_mul_f32 v[14:15], v[10:11], v[44:45] op_sel_hi:[1,0]
	v_pk_mul_f32 v[10:11], v[12:13], v[44:45] op_sel_hi:[1,0]
	v_mov_b32_e32 v16, v15
	v_mov_b32_e32 v17, v11
	v_mov_b32_e32 v12, v14
	v_mov_b32_e32 v13, v10
	v_pk_mul_f32 v[16:17], v[16:17], v[16:17]
	s_waitcnt vmcnt(0)
	v_fmac_f32_e32 v7, v6, v44
	v_mul_f32_e64 v6, |v7|, s15
	v_exp_f32_e32 v9, v6
	v_min_f32_e32 v8, 0, v7
	v_pk_fma_f32 v[12:13], v[12:13], v[12:13], v[16:17]
	v_add_f32_e32 v42, 1.0, v9
	v_add_f32_e32 v6, -1.0, v42
	v_sub_f32_e32 v7, v6, v42
	v_add_f32_e32 v7, 1.0, v7
	v_sub_f32_e32 v6, v9, v6
	v_add_f32_e32 v43, v6, v7
	v_frexp_mant_f32_e32 v6, v42
	v_cmp_gt_f32_e32 vcc, s19, v6
	v_cvt_f64_f32_e32 v[6:7], v42
	v_frexp_exp_i32_f64_e32 v6, v[6:7]
	v_subbrev_co_u32_e32 v6, vcc, 0, v6, vcc
	v_sub_u32_e32 v7, 0, v6
	v_ldexp_f32 v42, v42, v7
	v_ldexp_f32 v7, v43, v7
	v_add_f32_e32 v43, -1.0, v42
	v_add_f32_e32 v47, 1.0, v43
	v_sub_f32_e32 v47, v42, v47
	v_add_f32_e32 v47, v7, v47
	v_add_f32_e32 v48, v43, v47
	v_sub_f32_e32 v43, v48, v43
	v_sub_f32_e32 v43, v47, v43
	v_add_f32_e32 v47, 1.0, v42
	v_add_f32_e32 v49, -1.0, v47
	v_sub_f32_e32 v42, v42, v49
	v_add_f32_e32 v7, v7, v42
	v_add_f32_e32 v42, v47, v7
	v_sub_f32_e32 v47, v42, v47
	v_sub_f32_e32 v7, v7, v47
	v_rcp_f32_e32 v47, v42
	v_cvt_f32_i32_e32 v6, v6
	v_cmp_neq_f32_e32 vcc, s23, v9
	v_add_f32_e32 v12, v12, v13
	v_mul_f32_e32 v49, v48, v47
	v_mul_f32_e32 v50, v42, v49
	v_fma_f32 v51, v49, v42, -v50
	v_fmac_f32_e32 v51, v49, v7
	v_add_f32_e32 v52, v50, v51
	v_sub_f32_e32 v53, v48, v52
	v_sub_f32_e32 v48, v48, v53
	v_sub_f32_e32 v50, v52, v50
	v_sub_f32_e32 v48, v48, v52
	v_add_f32_e32 v43, v43, v48
	v_sub_f32_e32 v48, v50, v51
	v_add_f32_e32 v43, v48, v43
	v_add_f32_e32 v48, v53, v43
	v_mul_f32_e32 v50, v47, v48
	v_mul_f32_e32 v51, v42, v50
	v_fma_f32 v42, v50, v42, -v51
	v_fmac_f32_e32 v42, v50, v7
	v_sub_f32_e32 v7, v53, v48
	v_add_f32_e32 v7, v43, v7
	v_add_f32_e32 v43, v51, v42
	v_sub_f32_e32 v52, v48, v43
	v_sub_f32_e32 v48, v48, v52
	v_sub_f32_e32 v51, v43, v51
	v_sub_f32_e32 v43, v48, v43
	v_add_f32_e32 v7, v7, v43
	v_sub_f32_e32 v42, v51, v42
	v_add_f32_e32 v7, v42, v7
	v_add_f32_e32 v42, v49, v50
	v_add_f32_e32 v7, v52, v7
	v_sub_f32_e32 v43, v42, v49
	v_mul_f32_e32 v7, v47, v7
	v_sub_f32_e32 v43, v50, v43
	v_add_f32_e32 v7, v43, v7
	v_mul_f32_e32 v49, 0x3f317218, v6
	v_add_f32_e32 v43, v42, v7
	v_fma_f32 v50, v6, s22, -v49
	v_mul_f32_e32 v47, v43, v43
	v_fmac_f32_e32 v50, 0xb102e308, v6
	v_sub_f32_e32 v6, v43, v42
	v_fmamk_f32 v48, v47, 0x3e9b6dac, v183
	v_sub_f32_e32 v6, v7, v6
	v_add_f32_e32 v7, v49, v50
	v_fmaak_f32 v48, v47, v48, 0x3f2aaada
	v_sub_f32_e32 v42, v7, v49
	v_ldexp_f32 v49, v43, 1
	v_mul_f32_e32 v43, v43, v47
	v_mul_f32_e32 v43, v43, v48
	v_add_f32_e32 v47, v49, v43
	v_sub_f32_e32 v48, v47, v49
	v_ldexp_f32 v6, v6, 1
	v_sub_f32_e32 v43, v43, v48
	v_add_f32_e32 v6, v6, v43
	v_add_f32_e32 v43, v47, v6
	v_sub_f32_e32 v47, v43, v47
	v_sub_f32_e32 v6, v6, v47
	v_add_f32_e32 v47, v7, v43
	v_sub_f32_e32 v48, v47, v7
	v_sub_f32_e32 v49, v47, v48
	v_sub_f32_e32 v42, v50, v42
	v_sub_f32_e32 v7, v7, v49
	v_sub_f32_e32 v43, v43, v48
	v_add_f32_e32 v7, v43, v7
	v_add_f32_e32 v43, v42, v6
	v_sub_f32_e32 v48, v43, v42
	v_sub_f32_e32 v49, v43, v48
	v_sub_f32_e32 v42, v42, v49
	v_sub_f32_e32 v6, v6, v48
	v_add_f32_e32 v7, v43, v7
	v_add_f32_e32 v6, v6, v42
	v_add_f32_e32 v42, v47, v7
	v_sub_f32_e32 v43, v42, v47
	v_sub_f32_e32 v7, v7, v43
	v_add_f32_e32 v6, v6, v7
	v_add_f32_e32 v6, v42, v6
	v_cndmask_b32_e32 v6, v184, v6, vcc
	v_cmp_ngt_f32_e32 vcc, -1.0, v9
	v_add_u32_e32 v47, 0xffffe040, v152
	ds_swizzle_b32 v13, v12 offset:swizzle(SWAP,1)
	v_cndmask_b32_e32 v6, v185, v6, vcc
	v_cmp_neq_f32_e32 vcc, -1.0, v9
	s_waitcnt lgkmcnt(0)
	v_add_f32_e32 v12, v12, v13
	v_cndmask_b32_e32 v6, v247, v6, vcc
	v_cmp_lt_f32_e64 vcc, |v9|, s33
	ds_swizzle_b32 v13, v12 offset:swizzle(SWAP,2)
	s_waitcnt lgkmcnt(0)
	v_add_f32_e32 v12, v12, v13
	v_cndmask_b32_e32 v6, v6, v9, vcc
	v_sub_f32_e32 v48, v8, v6
	v_lshl_or_b32 v6, v45, 4, v5
	v_ashrrev_i32_e32 v7, 31, v6
	v_cmp_lt_i32_e32 vcc, s0, v152
	v_lshl_add_u64 v[6:7], v[6:7], 2, s[6:7]
	global_store_dword v[6:7], v48, off
	v_cndmask_b32_e32 v42, v45, v47, vcc
	v_cndmask_b32_e32 v6, v252, v186, vcc
	v_mov_b32_e32 v7, v4
	v_cndmask_b32_e32 v9, v154, v155, vcc
	v_cndmask_b32_e32 v8, v179, v180, vcc
	v_lshl_add_u64 v[6:7], s[82:83], 0, v[6:7]
	v_ashrrev_i32_e32 v43, 31, v42
	v_lshl_add_u64 v[6:7], v[6:7], 0, v[8:9]
	v_lshlrev_b64 v[8:9], 6, v[42:43]
	v_lshl_add_u64 v[6:7], v[6:7], 0, v[8:9]
	v_lshl_add_u64 v[6:7], v[6:7], 0, v[2:3]
	global_store_dword v[6:7], v48, off
	global_load_dwordx2 v[16:17], v106, s[8:9]
	ds_swizzle_b32 v13, v12 offset:swizzle(SWAP,4)
	v_and_b32_e32 v5, 15, v42
	v_or_b32_e32 v6, 0x800, v5
	v_and_b32_e32 v7, 0x7ff, v45
	v_cndmask_b32_e32 v6, v7, v6, vcc
	s_waitcnt lgkmcnt(0)
	v_add_f32_e32 v12, v12, v13
	ds_swizzle_b32 v13, v12 offset:swizzle(SWAP,8)
	v_lshlrev_b32_e32 v6, 8, v6
	v_mov_b32_e32 v7, v4
	v_lshl_add_u64 v[6:7], v[150:151], 0, v[6:7]
	global_load_dwordx4 v[6:9], v[6:7], off
	s_waitcnt lgkmcnt(0)
	v_add_f32_e32 v12, v12, v13
	v_fmamk_f32 v12, v12, 0x3c800000, v246
	v_cmp_gt_f32_e64 s[0:1], s95, v12
	v_mul_f32_e32 v13, 0x4b800000, v12
	s_nop 0
	v_cndmask_b32_e64 v12, v12, v13, s[0:1]
	v_rsq_f32_e32 v12, v12
	s_nop 0
	v_mul_f32_e32 v13, 0x45800000, v12
	v_cndmask_b32_e64 v12, v12, v13, s[0:1]
	s_waitcnt vmcnt(1)
	v_pk_mul_f32 v[16:17], v[16:17], v[12:13] op_sel_hi:[1,0]
	s_nop 0
	v_pk_mul_f32 v[14:15], v[14:15], v[16:17]
	global_load_dwordx2 v[16:17], v106, s[8:9] offset:128
	s_waitcnt vmcnt(0)
	v_pk_mul_f32 v[12:13], v[16:17], v[12:13] op_sel_hi:[1,0]
	s_nop 0
	v_pk_mul_f32 v[10:11], v[10:11], v[12:13]
	v_mov_b32_e32 v13, v8
	v_mov_b32_e32 v8, v7
	v_mov_b32_e32 v12, v6
	v_pk_mul_f32 v[6:7], v[8:9], v[10:11]
	v_pk_mul_f32 v[8:9], v[8:9], v[14:15]
	v_pk_fma_f32 v[6:7], v[12:13], v[14:15], v[6:7] neg_lo:[0,0,1] neg_hi:[0,0,1]
	v_pk_fma_f32 v[8:9], v[12:13], v[10:11], v[8:9]
	v_cndmask_b32_e32 v10, v250, v251, vcc
	v_mov_b32_e32 v11, v4
	v_cndmask_b32_e32 v13, v102, v103, vcc
	v_cndmask_b32_e32 v12, v104, v105, vcc
	v_lshl_add_u64 v[10:11], s[82:83], 0, v[10:11]
	v_lshl_add_u64 v[10:11], v[10:11], 0, v[12:13]
	v_lshlrev_b64 v[12:13], 8, v[42:43]
	v_lshl_add_u64 v[10:11], v[10:11], 0, v[12:13]
	v_lshl_add_u64 v[10:11], v[10:11], 0, v[106:107]
	global_store_dwordx2 v[10:11], v[6:7], off
	global_store_dwordx2 v[10:11], v[8:9], off offset:128
	v_lshrrev_b32_e32 v10, 4, v47
	v_mul_lo_u32 v10, v10, s10
	v_or_b32_e32 v5, v10, v5
	v_add_u32_e32 v5, 0x800, v5
	v_cndmask_b32_e64 v11, v46, 0, vcc
	v_cndmask_b32_e32 v10, v45, v5, vcc
	v_cndmask_b32_e32 v13, v112, v113, vcc
	v_cndmask_b32_e32 v12, v114, v115, vcc
	v_lshlrev_b64 v[10:11], 7, v[10:11]
	v_lshl_add_u64 v[10:11], v[12:13], 0, v[10:11]
	v_cvt_pk_bf16_f32 v5, v6, v7
	v_lshl_add_u64 v[2:3], v[10:11], 0, v[2:3]
	global_store_dword v[2:3], v5, off
	v_cvt_pk_bf16_f32 v5, v8, v9
	global_store_dword v[2:3], v5, off offset:64
	s_barrier
